# S5 pass-2 items rewritten too: B*u on f32 matrix cores (v_mfma_f32_16x16x4_f32), f32 recurrence on the VALU, baseline bf16 output projection and gelu epilogue
# speedup vs baseline: 1.2930x; 1.0229x over previous
; __device__ __forceinline__ int otid() { int t = threadIdx.x; asm volatile("" : "+v"(t)); return t; }
; __device__ void phase_s5_pass2(CParams& p, int l, int item, char* smem) {
;   const int tid = otid(), lane = tid & 63, wid = tid >> 6;
;   int q = item >> 2, gq = item & 3;
;   int g = gq * 4 + wid;
;   float* us = (float*)smem + wid * 1024;
;   bf16_t* hs = (bf16_t*)(smem + 16384) + wid * (16 * 136);
;   int tok0 = q * 64;
;   __syncthreads();
;   {
;     const float* src = p.zs5 + (size_t)(tok0 + lane) * 256 + g * 16;
; #pragma unroll
;     for (int i = 0; i < 4; i++) *(float4*)(us + lane * 16 + i * 4) = *(const float4*)(src + i * 4);
;   }
;   __syncthreads();
;   f32x4 acc[4];
; #pragma unroll
;   for (int s = 0; s < 4; s++) acc[s] = f32x4{0.f, 0.f, 0.f, 0.f};
;   const int l15 = lane & 15, lq = lane >> 4;
; #pragma unroll
;   for (int dir = 0; dir < 2; dir++) {
;     int pidx = ((l * 2 + dir) * 16 + g) * 64 + lane;
;     float2 A = p.Apar[pidx];
;     f32x2 bb[16];
; #pragma unroll
;     for (int cc = 0; cc < 16; cc++) {
;       float2 b = p.Bbar[(size_t)pidx * 16 + cc];
;       bb[cc] = f32x2{b.x, b.y};
;     }
;     bf16x8 cf[4];
; #pragma unroll
;     for (int ks = 0; ks < 4; ks++) {
;       int k = ks * 32 + lq * 8;
;       bool im = k >= 64;
;       const float* src = (im ? p.c_im : p.c_re) + ((((size_t)(l * 2 + dir) * 16 + g) * 16 + l15) * 64) + (k & 63);
;       float4 v0 = *(const float4*)src, v1 = *(const float4*)(src + 4);
;       float sgn = im ? -1.f : 1.f;
;       cf[ks][0] = (short)f2bf(sgn * v0.x); cf[ks][1] = (short)f2bf(sgn * v0.y);
;       cf[ks][2] = (short)f2bf(sgn * v0.z); cf[ks][3] = (short)f2bf(sgn * v0.w);
;       cf[ks][4] = (short)f2bf(sgn * v1.x); cf[ks][5] = (short)f2bf(sgn * v1.y);
;       cf[ks][6] = (short)f2bf(sgn * v1.z); cf[ks][7] = (short)f2bf(sgn * v1.w);
;     }
;     float2 h0 = p.Hin[(((size_t)q * 2 + dir) * 16 + g) * 64 + lane];
;     float hr = h0.x, hi = h0.y;
.LBB0_701:
	s_load_dwordx2 s[6:7], s[44:45], 0x190
	s_load_dwordx2 s[8:9], s[44:45], 0x1b8
	v_readlane_b32 s12, v224, 26
	v_readfirstlane_b32 s4, v147
	v_and_b32_e32 v32, 63, v147
	s_lshr_b32 s1, s42, 2
	s_and_b32 s2, s42, 3
	s_lshl_b32 s2, s2, 2
	s_lshr_b32 s4, s4, 6
	s_add_u32 s2, s2, s4
	s_mov_b32 s99, 0x0
	s_cmp_eq_u32 s4, 1
	s_cselect_b32 s99, 0x3400, s99
	s_cmp_eq_u32 s4, 2
	s_cselect_b32 s99, 0x6800, s99
	s_cmp_eq_u32 s4, 3
	s_cselect_b32 s99, 0xa400, s99
	v_and_b32_e32 v33, 15, v32
	v_lshrrev_b32_e32 v34, 4, v32
	v_lshlrev_b32_e32 v40, 7, v33
	v_lshl_add_u32 v40, v34, 5, v40
	v_add_u32_e32 v41, 0x1000, v40
	v_lshlrev_b32_e32 v38, 11, v34
	v_lshl_add_u32 v38, v33, 3, v38
	v_add_u32_e32 v38, s99, v38
	v_add_u32_e32 v44, 0x0, v38
	v_add_u32_e32 v45, 0x200, v38
	v_add_u32_e32 v46, 0x400, v38
	v_add_u32_e32 v47, 0x600, v38
	v_lshlrev_b32_e32 v52, 3, v32
	v_add_u32_e32 v52, s99, v52
	v_lshlrev_b32_e32 v60, 1, v32
	v_add_u32_e32 v60, s99, v60
	v_add_u32_e32 v60, 0x2000, v60
	v_mul_u32_u24_e32 v61, 0x110, v33
	v_lshl_add_u32 v61, v34, 4, v61
	v_add_u32_e32 v61, s99, v61
	v_add_u32_e32 v61, 0x2000, v61
	v_lshlrev_b32_e32 v49, 8, v33
	v_lshl_add_u32 v49, v34, 5, v49
	v_lshlrev_b32_e32 v63, 12, v34
	v_lshl_add_u32 v63, v33, 2, v63
	v_lshlrev_b32_e32 v48, 11, v34
	v_lshl_add_u32 v48, v33, 1, v48
	v_mov_b32_e32 v148, 0
	v_mov_b32_e32 v149, 0
	v_mov_b32_e32 v150, 0
	v_mov_b32_e32 v151, 0
	v_mov_b32_e32 v152, 0
	v_mov_b32_e32 v153, 0
	v_mov_b32_e32 v154, 0
	v_mov_b32_e32 v155, 0
	v_mov_b32_e32 v156, 0
	v_mov_b32_e32 v157, 0
	v_mov_b32_e32 v158, 0
	v_mov_b32_e32 v159, 0
	v_mov_b32_e32 v160, 0
	v_mov_b32_e32 v161, 0
	v_mov_b32_e32 v162, 0
	v_mov_b32_e32 v163, 0
	s_waitcnt lgkmcnt(0)
	s_lshl_b32 s20, s1, 16
	s_lshl_b32 s32, s2, 6
	s_add_u32 s20, s20, s32
	s_add_u32 s6, s6, s20
	s_addc_u32 s7, s7, 0
	s_lshr_b32 s20, s20, 1
	s_add_u32 s8, s8, s20
	s_addc_u32 s9, s9, 0
	s_barrier
	s_lshl_b32 s20, s12, 1
	s_add_u32 s20, s20, 0
	s_lshl_b32 s20, s20, 4
	s_add_u32 s20, s20, s2
	s_lshl_b32 s19, s20, 6
	s_load_dwordx2 s[22:23], s[44:45], 0x168
	s_load_dwordx2 s[24:25], s[44:45], 0x170
	s_load_dwordx2 s[26:27], s[44:45], 0x68
	s_load_dwordx2 s[34:35], s[44:45], 0x70
	s_load_dwordx2 s[40:41], s[44:45], 0x180
	s_waitcnt lgkmcnt(0)
	s_lshl_b32 s20, s19, 3
	s_add_u32 s22, s22, s20
	s_addc_u32 s23, s23, 0
	s_lshl_b32 s20, s19, 7
	s_add_u32 s24, s24, s20
	s_addc_u32 s25, s25, 0
	s_lshl_b32 s20, s19, 6
	s_add_u32 s26, s26, s20
	s_addc_u32 s27, s27, 0
	s_add_u32 s34, s34, s20
	s_addc_u32 s35, s35, 0
	s_lshl_b32 s20, s1, 1
	s_add_u32 s20, s20, 0
	s_lshl_b32 s20, s20, 4
	s_add_u32 s20, s20, s2
	s_lshl_b32 s20, s20, 9
	s_add_u32 s40, s40, s20
	s_addc_u32 s41, s41, 0
	v_lshlrev_b32_e32 v38, 3, v32
	global_load_dwordx2 v[36:37], v38, s[22:23]
	global_load_dwordx2 v[54:55], v38, s[40:41]
	global_load_dwordx2 v[64:65], v40, s[24:25] offset:0
	global_load_dwordx2 v[66:67], v40, s[24:25] offset:8
	global_load_dwordx2 v[68:69], v40, s[24:25] offset:16
	global_load_dwordx2 v[70:71], v40, s[24:25] offset:24
	global_load_dwordx2 v[72:73], v40, s[24:25] offset:2048
	global_load_dwordx2 v[74:75], v40, s[24:25] offset:2056
	global_load_dwordx2 v[76:77], v40, s[24:25] offset:2064
	global_load_dwordx2 v[78:79], v40, s[24:25] offset:2072
	global_load_dwordx2 v[80:81], v41, s[24:25] offset:0
	global_load_dwordx2 v[82:83], v41, s[24:25] offset:8
	global_load_dwordx2 v[84:85], v41, s[24:25] offset:16
	global_load_dwordx2 v[86:87], v41, s[24:25] offset:24
	global_load_dwordx2 v[88:89], v41, s[24:25] offset:2048
	global_load_dwordx2 v[90:91], v41, s[24:25] offset:2056
	global_load_dwordx2 v[92:93], v41, s[24:25] offset:2064
	global_load_dwordx2 v[94:95], v41, s[24:25] offset:2072
	global_load_dwordx4 v[112:115], v49, s[26:27] offset:0
	global_load_dwordx4 v[116:119], v49, s[26:27] offset:16
	global_load_dwordx4 v[120:123], v49, s[26:27] offset:128
	global_load_dwordx4 v[124:127], v49, s[26:27] offset:144
	global_load_dwordx4 v[128:131], v49, s[34:35] offset:0
	global_load_dwordx4 v[132:135], v49, s[34:35] offset:16
	global_load_dwordx4 v[136:139], v49, s[34:35] offset:128
	global_load_dwordx4 v[140:143], v49, s[34:35] offset:144
	v_lshlrev_b32_e32 v42, 10, v33
	v_lshl_add_u32 v42, v34, 4, v42
	s_mov_b32 s98, 0x4000
	global_load_dwordx4 v[96:99], v42, s[6:7]
	v_add_u32_e32 v42, s98, v42
	global_load_dwordx4 v[100:103], v42, s[6:7]
	v_add_u32_e32 v42, s98, v42
	global_load_dwordx4 v[104:107], v42, s[6:7]
	v_add_u32_e32 v42, s98, v42
	global_load_dwordx4 v[108:111], v42, s[6:7]
	s_waitcnt vmcnt(4)
	v_cvt_pk_bf16_f32 v168, v112, v113
	v_cvt_pk_bf16_f32 v169, v114, v115
	v_cvt_pk_bf16_f32 v170, v116, v117
	v_cvt_pk_bf16_f32 v171, v118, v119
	v_cvt_pk_bf16_f32 v172, v120, v121
	v_cvt_pk_bf16_f32 v173, v122, v123
	v_cvt_pk_bf16_f32 v174, v124, v125
	v_cvt_pk_bf16_f32 v175, v126, v127
	v_cvt_pk_bf16_f32 v176, v128, v129
	v_xor_b32_e32 v176, 0x80008000, v176
	v_cvt_pk_bf16_f32 v177, v130, v131
	v_xor_b32_e32 v177, 0x80008000, v177
	v_cvt_pk_bf16_f32 v178, v132, v133
	v_xor_b32_e32 v178, 0x80008000, v178
	v_cvt_pk_bf16_f32 v179, v134, v135
	v_xor_b32_e32 v179, 0x80008000, v179
	v_cvt_pk_bf16_f32 v180, v136, v137
	v_xor_b32_e32 v180, 0x80008000, v180
	v_cvt_pk_bf16_f32 v181, v138, v139
	v_xor_b32_e32 v181, 0x80008000, v181
	v_cvt_pk_bf16_f32 v182, v140, v141
	v_xor_b32_e32 v182, 0x80008000, v182
	v_cvt_pk_bf16_f32 v183, v142, v143
	v_xor_b32_e32 v183, 0x80008000, v183
	s_waitcnt vmcnt(3)
; __device__ void phase_s5_pass2(CParams& p, int l, int item, char* smem) {
;     ...
; #pragma unroll
;     for (int s = 0; s < 4; s++) {
;       const int sb = dir == 0 ? s : 3 - s;
;       for (int i = 0; i < 16; i++) {
;         int tl = dir == 0 ? i : 15 - i;
;         int t = sb * 16 + tl;
;         float u[16];
; #pragma unroll
;         for (int k = 0; k < 4; k++) {
;           float4 uv = *(const float4*)(us + t * 16 + k * 4);
;           u[k * 4] = uv.x; u[k * 4 + 1] = uv.y; u[k * 4 + 2] = uv.z; u[k * 4 + 3] = uv.w;
;         }
;         f32x2 bu = {0.f, 0.f};
; #pragma unroll
;         for (int cc = 0; cc < 16; cc++) bu = __builtin_elementwise_fma(bb[cc], f32x2{u[cc], u[cc]}, bu);
;         float nr = A.x * hr - A.y * hi + bu[0];
;         float ni = A.x * hi + A.y * hr + bu[1];
;         hr = nr; hi = ni;
;         hs[tl * 136 + lane] = f2bf(hr);
;         hs[tl * 136 + 64 + lane] = f2bf(hi);
;       }
;       __syncthreads();
; #pragma unroll
;       for (int ks = 0; ks < 4; ks++) {
;         bf16x8 a = *(const bf16x8*)(hs + l15 * 136 + ks * 32 + lq * 8);
;         acc[sb] = __builtin_amdgcn_mfma_f32_16x16x32_bf16(a, cf[ks], acc[sb], 0, 0, 0);
;       }
	v_mfma_f32_16x16x4_f32 v[0:3], v96, v64, 0
	v_mfma_f32_16x16x4_f32 v[4:7], v96, v65, 0
	v_mfma_f32_16x16x4_f32 v[8:11], v96, v72, 0
	v_mfma_f32_16x16x4_f32 v[12:15], v96, v73, 0
	v_mfma_f32_16x16x4_f32 v[16:19], v96, v80, 0
	v_mfma_f32_16x16x4_f32 v[20:23], v96, v81, 0
	v_mfma_f32_16x16x4_f32 v[24:27], v96, v88, 0
	v_mfma_f32_16x16x4_f32 v[28:31], v96, v89, 0
	v_mfma_f32_16x16x4_f32 v[0:3], v97, v66, v[0:3]
	v_mfma_f32_16x16x4_f32 v[4:7], v97, v67, v[4:7]
	v_mfma_f32_16x16x4_f32 v[8:11], v97, v74, v[8:11]
	v_mfma_f32_16x16x4_f32 v[12:15], v97, v75, v[12:15]
	v_mfma_f32_16x16x4_f32 v[16:19], v97, v82, v[16:19]
	v_mfma_f32_16x16x4_f32 v[20:23], v97, v83, v[20:23]
	v_mfma_f32_16x16x4_f32 v[24:27], v97, v90, v[24:27]
	v_mfma_f32_16x16x4_f32 v[28:31], v97, v91, v[28:31]
	v_mfma_f32_16x16x4_f32 v[0:3], v98, v68, v[0:3]
	v_mfma_f32_16x16x4_f32 v[4:7], v98, v69, v[4:7]
	v_mfma_f32_16x16x4_f32 v[8:11], v98, v76, v[8:11]
	v_mfma_f32_16x16x4_f32 v[12:15], v98, v77, v[12:15]
	v_mfma_f32_16x16x4_f32 v[16:19], v98, v84, v[16:19]
	v_mfma_f32_16x16x4_f32 v[20:23], v98, v85, v[20:23]
	v_mfma_f32_16x16x4_f32 v[24:27], v98, v92, v[24:27]
	v_mfma_f32_16x16x4_f32 v[28:31], v98, v93, v[28:31]
	v_mfma_f32_16x16x4_f32 v[0:3], v99, v70, v[0:3]
	v_mfma_f32_16x16x4_f32 v[4:7], v99, v71, v[4:7]
	v_mfma_f32_16x16x4_f32 v[8:11], v99, v78, v[8:11]
	v_mfma_f32_16x16x4_f32 v[12:15], v99, v79, v[12:15]
	v_mfma_f32_16x16x4_f32 v[16:19], v99, v86, v[16:19]
	v_mfma_f32_16x16x4_f32 v[20:23], v99, v87, v[20:23]
	v_mfma_f32_16x16x4_f32 v[24:27], v99, v94, v[24:27]
	v_mfma_f32_16x16x4_f32 v[28:31], v99, v95, v[28:31]
	s_nop 15
	s_nop 15
	ds_write2_b32 v44, v0, v4 offset0:0 offset1:1
	ds_write2_b32 v45, v1, v5 offset0:0 offset1:1
	ds_write2_b32 v46, v2, v6 offset0:0 offset1:1
	ds_write2_b32 v47, v3, v7 offset0:0 offset1:1
	ds_write2_b32 v44, v8, v12 offset0:32 offset1:33
	ds_write2_b32 v45, v9, v13 offset0:32 offset1:33
	ds_write2_b32 v46, v10, v14 offset0:32 offset1:33
	ds_write2_b32 v47, v11, v15 offset0:32 offset1:33
	ds_write2_b32 v44, v16, v20 offset0:64 offset1:65
	ds_write2_b32 v45, v17, v21 offset0:64 offset1:65
	ds_write2_b32 v46, v18, v22 offset0:64 offset1:65
	ds_write2_b32 v47, v19, v23 offset0:64 offset1:65
	ds_write2_b32 v44, v24, v28 offset0:96 offset1:97
	ds_write2_b32 v45, v25, v29 offset0:96 offset1:97
	ds_write2_b32 v46, v26, v30 offset0:96 offset1:97
	ds_write2_b32 v47, v27, v31 offset0:96 offset1:97
	ds_read_b64 v[0:1], v52 offset:0
	ds_read_b64 v[2:3], v52 offset:512
	ds_read_b64 v[4:5], v52 offset:1024
	ds_read_b64 v[6:7], v52 offset:1536
	ds_read_b64 v[8:9], v52 offset:2048
	ds_read_b64 v[10:11], v52 offset:2560
	ds_read_b64 v[12:13], v52 offset:3072
	ds_read_b64 v[14:15], v52 offset:3584
	ds_read_b64 v[16:17], v52 offset:4096
	ds_read_b64 v[18:19], v52 offset:4608
	ds_read_b64 v[20:21], v52 offset:5120
	ds_read_b64 v[22:23], v52 offset:5632
	ds_read_b64 v[24:25], v52 offset:6144
	ds_read_b64 v[26:27], v52 offset:6656
	ds_read_b64 v[28:29], v52 offset:7168
	ds_read_b64 v[30:31], v52 offset:7680
	s_waitcnt vmcnt(2)
	s_waitcnt lgkmcnt(15)
	v_fma_f32 v58, v36, v54, v0
	v_fma_f32 v59, v36, v55, v1
	v_mfma_f32_16x16x4_f32 v[112:115], v100, v64, 0
	v_mfma_f32_16x16x4_f32 v[116:119], v100, v65, 0
	v_fma_f32 v56, -v37, v55, v58
	v_fma_f32 v57, v37, v54, v59
	v_cvt_pk_bf16_f32 v62, v56, v57
	ds_write_b16 v60, v62 offset:0
	ds_write_b16_d16_hi v60, v62 offset:128
	s_waitcnt lgkmcnt(15)
	v_fma_f32 v58, v36, v56, v2
	v_fma_f32 v59, v36, v57, v3
	v_mfma_f32_16x16x4_f32 v[120:123], v100, v72, 0
	v_mfma_f32_16x16x4_f32 v[124:127], v100, v73, 0
	v_fma_f32 v54, -v37, v57, v58
	v_fma_f32 v55, v37, v56, v59
	v_cvt_pk_bf16_f32 v62, v54, v55
	ds_write_b16 v60, v62 offset:272
	ds_write_b16_d16_hi v60, v62 offset:400
	s_waitcnt lgkmcnt(15)
	v_fma_f32 v58, v36, v54, v4
	v_fma_f32 v59, v36, v55, v5
	v_mfma_f32_16x16x4_f32 v[128:131], v100, v80, 0
	v_mfma_f32_16x16x4_f32 v[132:135], v100, v81, 0
	v_fma_f32 v56, -v37, v55, v58
	v_fma_f32 v57, v37, v54, v59
	v_cvt_pk_bf16_f32 v62, v56, v57
	ds_write_b16 v60, v62 offset:544
	ds_write_b16_d16_hi v60, v62 offset:672
	s_waitcnt lgkmcnt(15)
	v_fma_f32 v58, v36, v56, v6
	v_fma_f32 v59, v36, v57, v7
	v_mfma_f32_16x16x4_f32 v[136:139], v100, v88, 0
	v_mfma_f32_16x16x4_f32 v[140:143], v100, v89, 0
	v_fma_f32 v54, -v37, v57, v58
	v_fma_f32 v55, v37, v56, v59
	v_cvt_pk_bf16_f32 v62, v54, v55
	ds_write_b16 v60, v62 offset:816
	ds_write_b16_d16_hi v60, v62 offset:944
	s_waitcnt lgkmcnt(15)
	v_fma_f32 v58, v36, v54, v8
	v_fma_f32 v59, v36, v55, v9
	v_mfma_f32_16x16x4_f32 v[112:115], v101, v66, v[112:115]
	v_mfma_f32_16x16x4_f32 v[116:119], v101, v67, v[116:119]
	v_fma_f32 v56, -v37, v55, v58
	v_fma_f32 v57, v37, v54, v59
	v_cvt_pk_bf16_f32 v62, v56, v57
	ds_write_b16 v60, v62 offset:1088
	ds_write_b16_d16_hi v60, v62 offset:1216
	s_waitcnt lgkmcnt(15)
	v_fma_f32 v58, v36, v56, v10
	v_fma_f32 v59, v36, v57, v11
	v_mfma_f32_16x16x4_f32 v[120:123], v101, v74, v[120:123]
	v_mfma_f32_16x16x4_f32 v[124:127], v101, v75, v[124:127]
	v_fma_f32 v54, -v37, v57, v58
	v_fma_f32 v55, v37, v56, v59
	v_cvt_pk_bf16_f32 v62, v54, v55
	ds_write_b16 v60, v62 offset:1360
	ds_write_b16_d16_hi v60, v62 offset:1488
	s_waitcnt lgkmcnt(15)
	v_fma_f32 v58, v36, v54, v12
	v_fma_f32 v59, v36, v55, v13
	v_mfma_f32_16x16x4_f32 v[128:131], v101, v82, v[128:131]
	v_mfma_f32_16x16x4_f32 v[132:135], v101, v83, v[132:135]
	v_fma_f32 v56, -v37, v55, v58
	v_fma_f32 v57, v37, v54, v59
	v_cvt_pk_bf16_f32 v62, v56, v57
	ds_write_b16 v60, v62 offset:1632
	ds_write_b16_d16_hi v60, v62 offset:1760
	s_waitcnt lgkmcnt(15)
; __device__ void phase_s5_pass2(CParams& p, int l, int item, char* smem) {
;     ...
; #pragma unroll
;     for (int s = 0; s < 4; s++) {
;       const int sb = dir == 0 ? s : 3 - s;
;       for (int i = 0; i < 16; i++) {
;         int tl = dir == 0 ? i : 15 - i;
;         int t = sb * 16 + tl;
;         float u[16];
; #pragma unroll
;         for (int k = 0; k < 4; k++) {
;           float4 uv = *(const float4*)(us + t * 16 + k * 4);
;           u[k * 4] = uv.x; u[k * 4 + 1] = uv.y; u[k * 4 + 2] = uv.z; u[k * 4 + 3] = uv.w;
;         }
;         f32x2 bu = {0.f, 0.f};
; #pragma unroll
;         for (int cc = 0; cc < 16; cc++) bu = __builtin_elementwise_fma(bb[cc], f32x2{u[cc], u[cc]}, bu);
;         float nr = A.x * hr - A.y * hi + bu[0];
;         float ni = A.x * hi + A.y * hr + bu[1];
;         hr = nr; hi = ni;
;         hs[tl * 136 + lane] = f2bf(hr);
;         hs[tl * 136 + 64 + lane] = f2bf(hi);
;       }
;       __syncthreads();
; #pragma unroll
;       for (int ks = 0; ks < 4; ks++) {
;         bf16x8 a = *(const bf16x8*)(hs + l15 * 136 + ks * 32 + lq * 8);
;         acc[sb] = __builtin_amdgcn_mfma_f32_16x16x32_bf16(a, cf[ks], acc[sb], 0, 0, 0);
;       }
	v_fma_f32 v58, v36, v56, v14
	v_fma_f32 v59, v36, v57, v15
	v_mfma_f32_16x16x4_f32 v[136:139], v101, v90, v[136:139]
	v_mfma_f32_16x16x4_f32 v[140:143], v101, v91, v[140:143]
	v_fma_f32 v54, -v37, v57, v58
	v_fma_f32 v55, v37, v56, v59
	v_cvt_pk_bf16_f32 v62, v54, v55
	ds_write_b16 v60, v62 offset:1904
	ds_write_b16_d16_hi v60, v62 offset:2032
	s_waitcnt lgkmcnt(15)
	v_fma_f32 v58, v36, v54, v16
	v_fma_f32 v59, v36, v55, v17
	v_mfma_f32_16x16x4_f32 v[112:115], v102, v68, v[112:115]
	v_mfma_f32_16x16x4_f32 v[116:119], v102, v69, v[116:119]
	v_fma_f32 v56, -v37, v55, v58
	v_fma_f32 v57, v37, v54, v59
	v_cvt_pk_bf16_f32 v62, v56, v57
	ds_write_b16 v60, v62 offset:2176
	ds_write_b16_d16_hi v60, v62 offset:2304
	s_waitcnt lgkmcnt(15)
	v_fma_f32 v58, v36, v56, v18
	v_fma_f32 v59, v36, v57, v19
	v_mfma_f32_16x16x4_f32 v[120:123], v102, v76, v[120:123]
	v_mfma_f32_16x16x4_f32 v[124:127], v102, v77, v[124:127]
	v_fma_f32 v54, -v37, v57, v58
	v_fma_f32 v55, v37, v56, v59
	v_cvt_pk_bf16_f32 v62, v54, v55
	ds_write_b16 v60, v62 offset:2448
	ds_write_b16_d16_hi v60, v62 offset:2576
	s_waitcnt lgkmcnt(15)
	v_fma_f32 v58, v36, v54, v20
	v_fma_f32 v59, v36, v55, v21
	v_mfma_f32_16x16x4_f32 v[128:131], v102, v84, v[128:131]
	v_mfma_f32_16x16x4_f32 v[132:135], v102, v85, v[132:135]
	v_fma_f32 v56, -v37, v55, v58
	v_fma_f32 v57, v37, v54, v59
	v_cvt_pk_bf16_f32 v62, v56, v57
	ds_write_b16 v60, v62 offset:2720
	ds_write_b16_d16_hi v60, v62 offset:2848
	s_waitcnt lgkmcnt(15)
	v_fma_f32 v58, v36, v56, v22
	v_fma_f32 v59, v36, v57, v23
	v_mfma_f32_16x16x4_f32 v[136:139], v102, v92, v[136:139]
	v_mfma_f32_16x16x4_f32 v[140:143], v102, v93, v[140:143]
	v_fma_f32 v54, -v37, v57, v58
	v_fma_f32 v55, v37, v56, v59
	v_cvt_pk_bf16_f32 v62, v54, v55
	ds_write_b16 v60, v62 offset:2992
	ds_write_b16_d16_hi v60, v62 offset:3120
	s_waitcnt lgkmcnt(15)
	v_fma_f32 v58, v36, v54, v24
	v_fma_f32 v59, v36, v55, v25
	v_mfma_f32_16x16x4_f32 v[112:115], v103, v70, v[112:115]
	v_mfma_f32_16x16x4_f32 v[116:119], v103, v71, v[116:119]
	v_fma_f32 v56, -v37, v55, v58
	v_fma_f32 v57, v37, v54, v59
	v_cvt_pk_bf16_f32 v62, v56, v57
	ds_write_b16 v60, v62 offset:3264
	ds_write_b16_d16_hi v60, v62 offset:3392
	s_waitcnt lgkmcnt(15)
	v_fma_f32 v58, v36, v56, v26
	v_fma_f32 v59, v36, v57, v27
	v_mfma_f32_16x16x4_f32 v[120:123], v103, v78, v[120:123]
	v_mfma_f32_16x16x4_f32 v[124:127], v103, v79, v[124:127]
	v_fma_f32 v54, -v37, v57, v58
	v_fma_f32 v55, v37, v56, v59
	v_cvt_pk_bf16_f32 v62, v54, v55
	ds_write_b16 v60, v62 offset:3536
	ds_write_b16_d16_hi v60, v62 offset:3664
	s_waitcnt lgkmcnt(15)
	v_fma_f32 v58, v36, v54, v28
	v_fma_f32 v59, v36, v55, v29
	v_mfma_f32_16x16x4_f32 v[128:131], v103, v86, v[128:131]
	v_mfma_f32_16x16x4_f32 v[132:135], v103, v87, v[132:135]
	v_fma_f32 v56, -v37, v55, v58
	v_fma_f32 v57, v37, v54, v59
	v_cvt_pk_bf16_f32 v62, v56, v57
	ds_write_b16 v60, v62 offset:3808
	ds_write_b16_d16_hi v60, v62 offset:3936
	s_waitcnt lgkmcnt(15)
	v_fma_f32 v58, v36, v56, v30
	v_fma_f32 v59, v36, v57, v31
	v_mfma_f32_16x16x4_f32 v[136:139], v103, v94, v[136:139]
	v_mfma_f32_16x16x4_f32 v[140:143], v103, v95, v[140:143]
	v_fma_f32 v54, -v37, v57, v58
	v_fma_f32 v55, v37, v56, v59
	v_cvt_pk_bf16_f32 v62, v54, v55
	ds_write_b16 v60, v62 offset:4080
	ds_write_b16_d16_hi v60, v62 offset:4208
	ds_read_b128 v[184:187], v61 offset:0
	ds_read_b128 v[188:191], v61 offset:64
	ds_read_b128 v[192:195], v61 offset:128
	ds_read_b128 v[196:199], v61 offset:192
	s_waitcnt lgkmcnt(0)
	v_mfma_f32_16x16x32_bf16 v[148:151], v[184:187], v[168:171], v[148:151]
	v_mfma_f32_16x16x32_bf16 v[148:151], v[188:191], v[172:175], v[148:151]
	v_mfma_f32_16x16x32_bf16 v[148:151], v[192:195], v[176:179], v[148:151]
	v_mfma_f32_16x16x32_bf16 v[148:151], v[196:199], v[180:183], v[148:151]
	s_nop 15
	s_nop 15
	ds_write2_b32 v44, v112, v116 offset0:0 offset1:1
	ds_write2_b32 v45, v113, v117 offset0:0 offset1:1
	ds_write2_b32 v46, v114, v118 offset0:0 offset1:1
	ds_write2_b32 v47, v115, v119 offset0:0 offset1:1
	ds_write2_b32 v44, v120, v124 offset0:32 offset1:33
	ds_write2_b32 v45, v121, v125 offset0:32 offset1:33
	ds_write2_b32 v46, v122, v126 offset0:32 offset1:33
	ds_write2_b32 v47, v123, v127 offset0:32 offset1:33
	ds_write2_b32 v44, v128, v132 offset0:64 offset1:65
	ds_write2_b32 v45, v129, v133 offset0:64 offset1:65
	ds_write2_b32 v46, v130, v134 offset0:64 offset1:65
	ds_write2_b32 v47, v131, v135 offset0:64 offset1:65
	ds_write2_b32 v44, v136, v140 offset0:96 offset1:97
	ds_write2_b32 v45, v137, v141 offset0:96 offset1:97
	ds_write2_b32 v46, v138, v142 offset0:96 offset1:97
	ds_write2_b32 v47, v139, v143 offset0:96 offset1:97
	ds_read_b64 v[112:113], v52 offset:0
	ds_read_b64 v[114:115], v52 offset:512
	ds_read_b64 v[116:117], v52 offset:1024
	ds_read_b64 v[118:119], v52 offset:1536
	ds_read_b64 v[120:121], v52 offset:2048
	ds_read_b64 v[122:123], v52 offset:2560
	ds_read_b64 v[124:125], v52 offset:3072
	ds_read_b64 v[126:127], v52 offset:3584
	ds_read_b64 v[128:129], v52 offset:4096
	ds_read_b64 v[130:131], v52 offset:4608
	ds_read_b64 v[132:133], v52 offset:5120
	ds_read_b64 v[134:135], v52 offset:5632
	ds_read_b64 v[136:137], v52 offset:6144
	ds_read_b64 v[138:139], v52 offset:6656
	ds_read_b64 v[140:141], v52 offset:7168
	ds_read_b64 v[142:143], v52 offset:7680
	s_waitcnt vmcnt(1)
	s_waitcnt lgkmcnt(15)
	v_fma_f32 v58, v36, v54, v112
	v_fma_f32 v59, v36, v55, v113
	v_mfma_f32_16x16x4_f32 v[0:3], v104, v64, 0
	v_mfma_f32_16x16x4_f32 v[4:7], v104, v65, 0
	v_fma_f32 v56, -v37, v55, v58
	v_fma_f32 v57, v37, v54, v59
	v_cvt_pk_bf16_f32 v62, v56, v57
	ds_write_b16 v60, v62 offset:0
	ds_write_b16_d16_hi v60, v62 offset:128
	s_waitcnt lgkmcnt(15)
; __device__ void phase_s5_pass2(CParams& p, int l, int item, char* smem) {
;     ...
; #pragma unroll
;     for (int s = 0; s < 4; s++) {
;       const int sb = dir == 0 ? s : 3 - s;
;       for (int i = 0; i < 16; i++) {
;         int tl = dir == 0 ? i : 15 - i;
;         int t = sb * 16 + tl;
;         float u[16];
; #pragma unroll
;         for (int k = 0; k < 4; k++) {
;           float4 uv = *(const float4*)(us + t * 16 + k * 4);
;           u[k * 4] = uv.x; u[k * 4 + 1] = uv.y; u[k * 4 + 2] = uv.z; u[k * 4 + 3] = uv.w;
;         }
;         f32x2 bu = {0.f, 0.f};
; #pragma unroll
;         for (int cc = 0; cc < 16; cc++) bu = __builtin_elementwise_fma(bb[cc], f32x2{u[cc], u[cc]}, bu);
;         float nr = A.x * hr - A.y * hi + bu[0];
;         float ni = A.x * hi + A.y * hr + bu[1];
;         hr = nr; hi = ni;
;         hs[tl * 136 + lane] = f2bf(hr);
;         hs[tl * 136 + 64 + lane] = f2bf(hi);
;       }
;       __syncthreads();
; #pragma unroll
;       for (int ks = 0; ks < 4; ks++) {
;         bf16x8 a = *(const bf16x8*)(hs + l15 * 136 + ks * 32 + lq * 8);
;         acc[sb] = __builtin_amdgcn_mfma_f32_16x16x32_bf16(a, cf[ks], acc[sb], 0, 0, 0);
;       }
	v_fma_f32 v58, v36, v56, v114
	v_fma_f32 v59, v36, v57, v115
	v_mfma_f32_16x16x4_f32 v[8:11], v104, v72, 0
	v_mfma_f32_16x16x4_f32 v[12:15], v104, v73, 0
	v_fma_f32 v54, -v37, v57, v58
	v_fma_f32 v55, v37, v56, v59
	v_cvt_pk_bf16_f32 v62, v54, v55
	ds_write_b16 v60, v62 offset:272
	ds_write_b16_d16_hi v60, v62 offset:400
	s_waitcnt lgkmcnt(15)
	v_fma_f32 v58, v36, v54, v116
	v_fma_f32 v59, v36, v55, v117
	v_mfma_f32_16x16x4_f32 v[16:19], v104, v80, 0
	v_mfma_f32_16x16x4_f32 v[20:23], v104, v81, 0
	v_fma_f32 v56, -v37, v55, v58
	v_fma_f32 v57, v37, v54, v59
	v_cvt_pk_bf16_f32 v62, v56, v57
	ds_write_b16 v60, v62 offset:544
	ds_write_b16_d16_hi v60, v62 offset:672
	s_waitcnt lgkmcnt(15)
	v_fma_f32 v58, v36, v56, v118
	v_fma_f32 v59, v36, v57, v119
	v_mfma_f32_16x16x4_f32 v[24:27], v104, v88, 0
	v_mfma_f32_16x16x4_f32 v[28:31], v104, v89, 0
	v_fma_f32 v54, -v37, v57, v58
	v_fma_f32 v55, v37, v56, v59
	v_cvt_pk_bf16_f32 v62, v54, v55
	ds_write_b16 v60, v62 offset:816
	ds_write_b16_d16_hi v60, v62 offset:944
	s_waitcnt lgkmcnt(15)
	v_fma_f32 v58, v36, v54, v120
	v_fma_f32 v59, v36, v55, v121
	v_mfma_f32_16x16x4_f32 v[0:3], v105, v66, v[0:3]
	v_mfma_f32_16x16x4_f32 v[4:7], v105, v67, v[4:7]
	v_fma_f32 v56, -v37, v55, v58
	v_fma_f32 v57, v37, v54, v59
	v_cvt_pk_bf16_f32 v62, v56, v57
	ds_write_b16 v60, v62 offset:1088
	ds_write_b16_d16_hi v60, v62 offset:1216
	s_waitcnt lgkmcnt(15)
	v_fma_f32 v58, v36, v56, v122
	v_fma_f32 v59, v36, v57, v123
	v_mfma_f32_16x16x4_f32 v[8:11], v105, v74, v[8:11]
	v_mfma_f32_16x16x4_f32 v[12:15], v105, v75, v[12:15]
	v_fma_f32 v54, -v37, v57, v58
	v_fma_f32 v55, v37, v56, v59
	v_cvt_pk_bf16_f32 v62, v54, v55
	ds_write_b16 v60, v62 offset:1360
	ds_write_b16_d16_hi v60, v62 offset:1488
	s_waitcnt lgkmcnt(15)
	v_fma_f32 v58, v36, v54, v124
	v_fma_f32 v59, v36, v55, v125
	v_mfma_f32_16x16x4_f32 v[16:19], v105, v82, v[16:19]
	v_mfma_f32_16x16x4_f32 v[20:23], v105, v83, v[20:23]
	v_fma_f32 v56, -v37, v55, v58
	v_fma_f32 v57, v37, v54, v59
	v_cvt_pk_bf16_f32 v62, v56, v57
	ds_write_b16 v60, v62 offset:1632
	ds_write_b16_d16_hi v60, v62 offset:1760
	s_waitcnt lgkmcnt(15)
	v_fma_f32 v58, v36, v56, v126
	v_fma_f32 v59, v36, v57, v127
	v_mfma_f32_16x16x4_f32 v[24:27], v105, v90, v[24:27]
	v_mfma_f32_16x16x4_f32 v[28:31], v105, v91, v[28:31]
	v_fma_f32 v54, -v37, v57, v58
	v_fma_f32 v55, v37, v56, v59
	v_cvt_pk_bf16_f32 v62, v54, v55
	ds_write_b16 v60, v62 offset:1904
	ds_write_b16_d16_hi v60, v62 offset:2032
	s_waitcnt lgkmcnt(15)
	v_fma_f32 v58, v36, v54, v128
	v_fma_f32 v59, v36, v55, v129
	v_mfma_f32_16x16x4_f32 v[0:3], v106, v68, v[0:3]
	v_mfma_f32_16x16x4_f32 v[4:7], v106, v69, v[4:7]
	v_fma_f32 v56, -v37, v55, v58
	v_fma_f32 v57, v37, v54, v59
	v_cvt_pk_bf16_f32 v62, v56, v57
	ds_write_b16 v60, v62 offset:2176
	ds_write_b16_d16_hi v60, v62 offset:2304
	s_waitcnt lgkmcnt(15)
	v_fma_f32 v58, v36, v56, v130
	v_fma_f32 v59, v36, v57, v131
	v_mfma_f32_16x16x4_f32 v[8:11], v106, v76, v[8:11]
	v_mfma_f32_16x16x4_f32 v[12:15], v106, v77, v[12:15]
	v_fma_f32 v54, -v37, v57, v58
	v_fma_f32 v55, v37, v56, v59
	v_cvt_pk_bf16_f32 v62, v54, v55
	ds_write_b16 v60, v62 offset:2448
	ds_write_b16_d16_hi v60, v62 offset:2576
	s_waitcnt lgkmcnt(15)
	v_fma_f32 v58, v36, v54, v132
	v_fma_f32 v59, v36, v55, v133
	v_mfma_f32_16x16x4_f32 v[16:19], v106, v84, v[16:19]
	v_mfma_f32_16x16x4_f32 v[20:23], v106, v85, v[20:23]
	v_fma_f32 v56, -v37, v55, v58
	v_fma_f32 v57, v37, v54, v59
	v_cvt_pk_bf16_f32 v62, v56, v57
	ds_write_b16 v60, v62 offset:2720
	ds_write_b16_d16_hi v60, v62 offset:2848
	s_waitcnt lgkmcnt(15)
	v_fma_f32 v58, v36, v56, v134
	v_fma_f32 v59, v36, v57, v135
	v_mfma_f32_16x16x4_f32 v[24:27], v106, v92, v[24:27]
	v_mfma_f32_16x16x4_f32 v[28:31], v106, v93, v[28:31]
	v_fma_f32 v54, -v37, v57, v58
	v_fma_f32 v55, v37, v56, v59
	v_cvt_pk_bf16_f32 v62, v54, v55
	ds_write_b16 v60, v62 offset:2992
	ds_write_b16_d16_hi v60, v62 offset:3120
	s_waitcnt lgkmcnt(15)
	v_fma_f32 v58, v36, v54, v136
	v_fma_f32 v59, v36, v55, v137
	v_mfma_f32_16x16x4_f32 v[0:3], v107, v70, v[0:3]
	v_mfma_f32_16x16x4_f32 v[4:7], v107, v71, v[4:7]
	v_fma_f32 v56, -v37, v55, v58
	v_fma_f32 v57, v37, v54, v59
	v_cvt_pk_bf16_f32 v62, v56, v57
	ds_write_b16 v60, v62 offset:3264
	ds_write_b16_d16_hi v60, v62 offset:3392
	s_waitcnt lgkmcnt(15)
	v_fma_f32 v58, v36, v56, v138
	v_fma_f32 v59, v36, v57, v139
	v_mfma_f32_16x16x4_f32 v[8:11], v107, v78, v[8:11]
	v_mfma_f32_16x16x4_f32 v[12:15], v107, v79, v[12:15]
	v_fma_f32 v54, -v37, v57, v58
	v_fma_f32 v55, v37, v56, v59
	v_cvt_pk_bf16_f32 v62, v54, v55
	ds_write_b16 v60, v62 offset:3536
	ds_write_b16_d16_hi v60, v62 offset:3664
	s_waitcnt lgkmcnt(15)
	v_fma_f32 v58, v36, v54, v140
	v_fma_f32 v59, v36, v55, v141
	v_mfma_f32_16x16x4_f32 v[16:19], v107, v86, v[16:19]
	v_mfma_f32_16x16x4_f32 v[20:23], v107, v87, v[20:23]
	v_fma_f32 v56, -v37, v55, v58
	v_fma_f32 v57, v37, v54, v59
	v_cvt_pk_bf16_f32 v62, v56, v57
	ds_write_b16 v60, v62 offset:3808
	ds_write_b16_d16_hi v60, v62 offset:3936
	s_waitcnt lgkmcnt(15)
	v_fma_f32 v58, v36, v56, v142
	v_fma_f32 v59, v36, v57, v143
	v_mfma_f32_16x16x4_f32 v[24:27], v107, v94, v[24:27]
	v_mfma_f32_16x16x4_f32 v[28:31], v107, v95, v[28:31]
	v_fma_f32 v54, -v37, v57, v58
	v_fma_f32 v55, v37, v56, v59
	v_cvt_pk_bf16_f32 v62, v54, v55
	ds_write_b16 v60, v62 offset:4080
	ds_write_b16_d16_hi v60, v62 offset:4208
	ds_read_b128 v[184:187], v61 offset:0
	ds_read_b128 v[188:191], v61 offset:64
	ds_read_b128 v[192:195], v61 offset:128
	ds_read_b128 v[196:199], v61 offset:192
	s_waitcnt lgkmcnt(0)
; __device__ void phase_s5_pass2(CParams& p, int l, int item, char* smem) {
;     ...
; #pragma unroll
;     for (int s = 0; s < 4; s++) {
;       const int sb = dir == 0 ? s : 3 - s;
;       for (int i = 0; i < 16; i++) {
;         int tl = dir == 0 ? i : 15 - i;
;         int t = sb * 16 + tl;
;         float u[16];
; #pragma unroll
;         for (int k = 0; k < 4; k++) {
;           float4 uv = *(const float4*)(us + t * 16 + k * 4);
;           u[k * 4] = uv.x; u[k * 4 + 1] = uv.y; u[k * 4 + 2] = uv.z; u[k * 4 + 3] = uv.w;
;         }
;         f32x2 bu = {0.f, 0.f};
; #pragma unroll
;         for (int cc = 0; cc < 16; cc++) bu = __builtin_elementwise_fma(bb[cc], f32x2{u[cc], u[cc]}, bu);
;         float nr = A.x * hr - A.y * hi + bu[0];
;         float ni = A.x * hi + A.y * hr + bu[1];
;         hr = nr; hi = ni;
;         hs[tl * 136 + lane] = f2bf(hr);
;         hs[tl * 136 + 64 + lane] = f2bf(hi);
;       }
;       __syncthreads();
; #pragma unroll
;       for (int ks = 0; ks < 4; ks++) {
;         bf16x8 a = *(const bf16x8*)(hs + l15 * 136 + ks * 32 + lq * 8);
;         acc[sb] = __builtin_amdgcn_mfma_f32_16x16x32_bf16(a, cf[ks], acc[sb], 0, 0, 0);
;       }
	v_mfma_f32_16x16x32_bf16 v[152:155], v[184:187], v[168:171], v[152:155]
	v_mfma_f32_16x16x32_bf16 v[152:155], v[188:191], v[172:175], v[152:155]
	v_mfma_f32_16x16x32_bf16 v[152:155], v[192:195], v[176:179], v[152:155]
	v_mfma_f32_16x16x32_bf16 v[152:155], v[196:199], v[180:183], v[152:155]
	s_nop 15
	s_nop 15
	ds_write2_b32 v44, v0, v4 offset0:0 offset1:1
	ds_write2_b32 v45, v1, v5 offset0:0 offset1:1
	ds_write2_b32 v46, v2, v6 offset0:0 offset1:1
	ds_write2_b32 v47, v3, v7 offset0:0 offset1:1
	ds_write2_b32 v44, v8, v12 offset0:32 offset1:33
	ds_write2_b32 v45, v9, v13 offset0:32 offset1:33
	ds_write2_b32 v46, v10, v14 offset0:32 offset1:33
	ds_write2_b32 v47, v11, v15 offset0:32 offset1:33
	ds_write2_b32 v44, v16, v20 offset0:64 offset1:65
	ds_write2_b32 v45, v17, v21 offset0:64 offset1:65
	ds_write2_b32 v46, v18, v22 offset0:64 offset1:65
	ds_write2_b32 v47, v19, v23 offset0:64 offset1:65
	ds_write2_b32 v44, v24, v28 offset0:96 offset1:97
	ds_write2_b32 v45, v25, v29 offset0:96 offset1:97
	ds_write2_b32 v46, v26, v30 offset0:96 offset1:97
	ds_write2_b32 v47, v27, v31 offset0:96 offset1:97
	ds_read_b64 v[0:1], v52 offset:0
	ds_read_b64 v[2:3], v52 offset:512
	ds_read_b64 v[4:5], v52 offset:1024
	ds_read_b64 v[6:7], v52 offset:1536
	ds_read_b64 v[8:9], v52 offset:2048
	ds_read_b64 v[10:11], v52 offset:2560
	ds_read_b64 v[12:13], v52 offset:3072
	ds_read_b64 v[14:15], v52 offset:3584
	ds_read_b64 v[16:17], v52 offset:4096
	ds_read_b64 v[18:19], v52 offset:4608
	ds_read_b64 v[20:21], v52 offset:5120
	ds_read_b64 v[22:23], v52 offset:5632
	ds_read_b64 v[24:25], v52 offset:6144
	ds_read_b64 v[26:27], v52 offset:6656
	ds_read_b64 v[28:29], v52 offset:7168
	ds_read_b64 v[30:31], v52 offset:7680
	s_waitcnt vmcnt(0)
	s_waitcnt lgkmcnt(15)
	v_fma_f32 v58, v36, v54, v0
	v_fma_f32 v59, v36, v55, v1
	v_mfma_f32_16x16x4_f32 v[112:115], v108, v64, 0
	v_mfma_f32_16x16x4_f32 v[116:119], v108, v65, 0
	v_fma_f32 v56, -v37, v55, v58
	v_fma_f32 v57, v37, v54, v59
	v_cvt_pk_bf16_f32 v62, v56, v57
	ds_write_b16 v60, v62 offset:0
	ds_write_b16_d16_hi v60, v62 offset:128
	s_waitcnt lgkmcnt(15)
	v_fma_f32 v58, v36, v56, v2
	v_fma_f32 v59, v36, v57, v3
	v_mfma_f32_16x16x4_f32 v[120:123], v108, v72, 0
	v_mfma_f32_16x16x4_f32 v[124:127], v108, v73, 0
	v_fma_f32 v54, -v37, v57, v58
	v_fma_f32 v55, v37, v56, v59
	v_cvt_pk_bf16_f32 v62, v54, v55
	ds_write_b16 v60, v62 offset:272
	ds_write_b16_d16_hi v60, v62 offset:400
	s_waitcnt lgkmcnt(15)
	v_fma_f32 v58, v36, v54, v4
	v_fma_f32 v59, v36, v55, v5
	v_mfma_f32_16x16x4_f32 v[128:131], v108, v80, 0
	v_mfma_f32_16x16x4_f32 v[132:135], v108, v81, 0
	v_fma_f32 v56, -v37, v55, v58
	v_fma_f32 v57, v37, v54, v59
	v_cvt_pk_bf16_f32 v62, v56, v57
	ds_write_b16 v60, v62 offset:544
	ds_write_b16_d16_hi v60, v62 offset:672
	s_waitcnt lgkmcnt(15)
	v_fma_f32 v58, v36, v56, v6
	v_fma_f32 v59, v36, v57, v7
	v_mfma_f32_16x16x4_f32 v[136:139], v108, v88, 0
	v_mfma_f32_16x16x4_f32 v[140:143], v108, v89, 0
	v_fma_f32 v54, -v37, v57, v58
	v_fma_f32 v55, v37, v56, v59
	v_cvt_pk_bf16_f32 v62, v54, v55
	ds_write_b16 v60, v62 offset:816
	ds_write_b16_d16_hi v60, v62 offset:944
	s_waitcnt lgkmcnt(15)
	v_fma_f32 v58, v36, v54, v8
	v_fma_f32 v59, v36, v55, v9
	v_mfma_f32_16x16x4_f32 v[112:115], v109, v66, v[112:115]
	v_mfma_f32_16x16x4_f32 v[116:119], v109, v67, v[116:119]
	v_fma_f32 v56, -v37, v55, v58
	v_fma_f32 v57, v37, v54, v59
	v_cvt_pk_bf16_f32 v62, v56, v57
	ds_write_b16 v60, v62 offset:1088
	ds_write_b16_d16_hi v60, v62 offset:1216
	s_waitcnt lgkmcnt(15)
	v_fma_f32 v58, v36, v56, v10
	v_fma_f32 v59, v36, v57, v11
	v_mfma_f32_16x16x4_f32 v[120:123], v109, v74, v[120:123]
	v_mfma_f32_16x16x4_f32 v[124:127], v109, v75, v[124:127]
	v_fma_f32 v54, -v37, v57, v58
	v_fma_f32 v55, v37, v56, v59
	v_cvt_pk_bf16_f32 v62, v54, v55
	ds_write_b16 v60, v62 offset:1360
	ds_write_b16_d16_hi v60, v62 offset:1488
	s_waitcnt lgkmcnt(15)
	v_fma_f32 v58, v36, v54, v12
	v_fma_f32 v59, v36, v55, v13
	v_mfma_f32_16x16x4_f32 v[128:131], v109, v82, v[128:131]
	v_mfma_f32_16x16x4_f32 v[132:135], v109, v83, v[132:135]
	v_fma_f32 v56, -v37, v55, v58
	v_fma_f32 v57, v37, v54, v59
	v_cvt_pk_bf16_f32 v62, v56, v57
	ds_write_b16 v60, v62 offset:1632
	ds_write_b16_d16_hi v60, v62 offset:1760
	s_waitcnt lgkmcnt(15)
	v_fma_f32 v58, v36, v56, v14
	v_fma_f32 v59, v36, v57, v15
	v_mfma_f32_16x16x4_f32 v[136:139], v109, v90, v[136:139]
	v_mfma_f32_16x16x4_f32 v[140:143], v109, v91, v[140:143]
	v_fma_f32 v54, -v37, v57, v58
	v_fma_f32 v55, v37, v56, v59
	v_cvt_pk_bf16_f32 v62, v54, v55
	ds_write_b16 v60, v62 offset:1904
	ds_write_b16_d16_hi v60, v62 offset:2032
	s_waitcnt lgkmcnt(15)
	v_fma_f32 v58, v36, v54, v16
	v_fma_f32 v59, v36, v55, v17
	v_mfma_f32_16x16x4_f32 v[112:115], v110, v68, v[112:115]
	v_mfma_f32_16x16x4_f32 v[116:119], v110, v69, v[116:119]
	v_fma_f32 v56, -v37, v55, v58
	v_fma_f32 v57, v37, v54, v59
	v_cvt_pk_bf16_f32 v62, v56, v57
	ds_write_b16 v60, v62 offset:2176
	ds_write_b16_d16_hi v60, v62 offset:2304
	s_waitcnt lgkmcnt(15)
	v_fma_f32 v58, v36, v56, v18
	v_fma_f32 v59, v36, v57, v19
	v_mfma_f32_16x16x4_f32 v[120:123], v110, v76, v[120:123]
	v_mfma_f32_16x16x4_f32 v[124:127], v110, v77, v[124:127]
	v_fma_f32 v54, -v37, v57, v58
	v_fma_f32 v55, v37, v56, v59
	v_cvt_pk_bf16_f32 v62, v54, v55
	ds_write_b16 v60, v62 offset:2448
	ds_write_b16_d16_hi v60, v62 offset:2576
	s_waitcnt lgkmcnt(15)
	v_fma_f32 v58, v36, v54, v20
	v_fma_f32 v59, v36, v55, v21
	v_mfma_f32_16x16x4_f32 v[128:131], v110, v84, v[128:131]
	v_mfma_f32_16x16x4_f32 v[132:135], v110, v85, v[132:135]
	v_fma_f32 v56, -v37, v55, v58
	v_fma_f32 v57, v37, v54, v59
	v_cvt_pk_bf16_f32 v62, v56, v57
	ds_write_b16 v60, v62 offset:2720
	ds_write_b16_d16_hi v60, v62 offset:2848
	s_waitcnt lgkmcnt(15)
; __device__ void phase_s5_pass2(CParams& p, int l, int item, char* smem) {
;     ...
; #pragma unroll
;     for (int s = 0; s < 4; s++) {
;       const int sb = dir == 0 ? s : 3 - s;
;       for (int i = 0; i < 16; i++) {
;         int tl = dir == 0 ? i : 15 - i;
;         int t = sb * 16 + tl;
;         float u[16];
; #pragma unroll
;         for (int k = 0; k < 4; k++) {
;           float4 uv = *(const float4*)(us + t * 16 + k * 4);
;           u[k * 4] = uv.x; u[k * 4 + 1] = uv.y; u[k * 4 + 2] = uv.z; u[k * 4 + 3] = uv.w;
;         }
;         f32x2 bu = {0.f, 0.f};
; #pragma unroll
;         for (int cc = 0; cc < 16; cc++) bu = __builtin_elementwise_fma(bb[cc], f32x2{u[cc], u[cc]}, bu);
;         float nr = A.x * hr - A.y * hi + bu[0];
;         float ni = A.x * hi + A.y * hr + bu[1];
;         hr = nr; hi = ni;
;         hs[tl * 136 + lane] = f2bf(hr);
;         hs[tl * 136 + 64 + lane] = f2bf(hi);
;       }
;       __syncthreads();
; #pragma unroll
;       for (int ks = 0; ks < 4; ks++) {
;         bf16x8 a = *(const bf16x8*)(hs + l15 * 136 + ks * 32 + lq * 8);
;         acc[sb] = __builtin_amdgcn_mfma_f32_16x16x32_bf16(a, cf[ks], acc[sb], 0, 0, 0);
;       }
	v_fma_f32 v58, v36, v56, v22
	v_fma_f32 v59, v36, v57, v23
	v_mfma_f32_16x16x4_f32 v[136:139], v110, v92, v[136:139]
	v_mfma_f32_16x16x4_f32 v[140:143], v110, v93, v[140:143]
	v_fma_f32 v54, -v37, v57, v58
	v_fma_f32 v55, v37, v56, v59
	v_cvt_pk_bf16_f32 v62, v54, v55
	ds_write_b16 v60, v62 offset:2992
	ds_write_b16_d16_hi v60, v62 offset:3120
	s_waitcnt lgkmcnt(15)
	v_fma_f32 v58, v36, v54, v24
	v_fma_f32 v59, v36, v55, v25
	v_mfma_f32_16x16x4_f32 v[112:115], v111, v70, v[112:115]
	v_mfma_f32_16x16x4_f32 v[116:119], v111, v71, v[116:119]
	v_fma_f32 v56, -v37, v55, v58
	v_fma_f32 v57, v37, v54, v59
	v_cvt_pk_bf16_f32 v62, v56, v57
	ds_write_b16 v60, v62 offset:3264
	ds_write_b16_d16_hi v60, v62 offset:3392
	s_waitcnt lgkmcnt(15)
	v_fma_f32 v58, v36, v56, v26
	v_fma_f32 v59, v36, v57, v27
	v_mfma_f32_16x16x4_f32 v[120:123], v111, v78, v[120:123]
	v_mfma_f32_16x16x4_f32 v[124:127], v111, v79, v[124:127]
	v_fma_f32 v54, -v37, v57, v58
	v_fma_f32 v55, v37, v56, v59
	v_cvt_pk_bf16_f32 v62, v54, v55
	ds_write_b16 v60, v62 offset:3536
	ds_write_b16_d16_hi v60, v62 offset:3664
	s_waitcnt lgkmcnt(15)
	v_fma_f32 v58, v36, v54, v28
	v_fma_f32 v59, v36, v55, v29
	v_mfma_f32_16x16x4_f32 v[128:131], v111, v86, v[128:131]
	v_mfma_f32_16x16x4_f32 v[132:135], v111, v87, v[132:135]
	v_fma_f32 v56, -v37, v55, v58
	v_fma_f32 v57, v37, v54, v59
	v_cvt_pk_bf16_f32 v62, v56, v57
	ds_write_b16 v60, v62 offset:3808
	ds_write_b16_d16_hi v60, v62 offset:3936
	s_waitcnt lgkmcnt(15)
	v_fma_f32 v58, v36, v56, v30
	v_fma_f32 v59, v36, v57, v31
	v_mfma_f32_16x16x4_f32 v[136:139], v111, v94, v[136:139]
	v_mfma_f32_16x16x4_f32 v[140:143], v111, v95, v[140:143]
	v_fma_f32 v54, -v37, v57, v58
	v_fma_f32 v55, v37, v56, v59
	v_cvt_pk_bf16_f32 v62, v54, v55
	ds_write_b16 v60, v62 offset:4080
	ds_write_b16_d16_hi v60, v62 offset:4208
	ds_read_b128 v[184:187], v61 offset:0
	ds_read_b128 v[188:191], v61 offset:64
	ds_read_b128 v[192:195], v61 offset:128
	ds_read_b128 v[196:199], v61 offset:192
	s_waitcnt lgkmcnt(0)
	v_mfma_f32_16x16x32_bf16 v[156:159], v[184:187], v[168:171], v[156:159]
	v_mfma_f32_16x16x32_bf16 v[156:159], v[188:191], v[172:175], v[156:159]
	v_mfma_f32_16x16x32_bf16 v[156:159], v[192:195], v[176:179], v[156:159]
	v_mfma_f32_16x16x32_bf16 v[156:159], v[196:199], v[180:183], v[156:159]
	s_nop 15
	s_nop 15
	ds_write2_b32 v44, v112, v116 offset0:0 offset1:1
	ds_write2_b32 v45, v113, v117 offset0:0 offset1:1
	ds_write2_b32 v46, v114, v118 offset0:0 offset1:1
	ds_write2_b32 v47, v115, v119 offset0:0 offset1:1
	ds_write2_b32 v44, v120, v124 offset0:32 offset1:33
	ds_write2_b32 v45, v121, v125 offset0:32 offset1:33
	ds_write2_b32 v46, v122, v126 offset0:32 offset1:33
	ds_write2_b32 v47, v123, v127 offset0:32 offset1:33
	ds_write2_b32 v44, v128, v132 offset0:64 offset1:65
	ds_write2_b32 v45, v129, v133 offset0:64 offset1:65
	ds_write2_b32 v46, v130, v134 offset0:64 offset1:65
	ds_write2_b32 v47, v131, v135 offset0:64 offset1:65
	ds_write2_b32 v44, v136, v140 offset0:96 offset1:97
	ds_write2_b32 v45, v137, v141 offset0:96 offset1:97
	ds_write2_b32 v46, v138, v142 offset0:96 offset1:97
	ds_write2_b32 v47, v139, v143 offset0:96 offset1:97
	ds_read_b64 v[112:113], v52 offset:0
	ds_read_b64 v[114:115], v52 offset:512
	ds_read_b64 v[116:117], v52 offset:1024
	ds_read_b64 v[118:119], v52 offset:1536
	ds_read_b64 v[120:121], v52 offset:2048
	ds_read_b64 v[122:123], v52 offset:2560
	ds_read_b64 v[124:125], v52 offset:3072
	ds_read_b64 v[126:127], v52 offset:3584
	ds_read_b64 v[128:129], v52 offset:4096
	ds_read_b64 v[130:131], v52 offset:4608
	ds_read_b64 v[132:133], v52 offset:5120
	ds_read_b64 v[134:135], v52 offset:5632
	ds_read_b64 v[136:137], v52 offset:6144
	ds_read_b64 v[138:139], v52 offset:6656
	ds_read_b64 v[140:141], v52 offset:7168
	ds_read_b64 v[142:143], v52 offset:7680
	s_waitcnt lgkmcnt(15)
	v_fma_f32 v58, v36, v54, v112
	v_fma_f32 v59, v36, v55, v113
	v_fma_f32 v56, -v37, v55, v58
	v_fma_f32 v57, v37, v54, v59
	v_cvt_pk_bf16_f32 v62, v56, v57
	ds_write_b16 v60, v62 offset:0
	ds_write_b16_d16_hi v60, v62 offset:128
	s_waitcnt lgkmcnt(15)
	v_fma_f32 v58, v36, v56, v114
	v_fma_f32 v59, v36, v57, v115
	v_fma_f32 v54, -v37, v57, v58
	v_fma_f32 v55, v37, v56, v59
	v_cvt_pk_bf16_f32 v62, v54, v55
	ds_write_b16 v60, v62 offset:272
	ds_write_b16_d16_hi v60, v62 offset:400
	s_waitcnt lgkmcnt(15)
	v_fma_f32 v58, v36, v54, v116
	v_fma_f32 v59, v36, v55, v117
	v_fma_f32 v56, -v37, v55, v58
	v_fma_f32 v57, v37, v54, v59
	v_cvt_pk_bf16_f32 v62, v56, v57
	ds_write_b16 v60, v62 offset:544
	ds_write_b16_d16_hi v60, v62 offset:672
	s_waitcnt lgkmcnt(15)
	v_fma_f32 v58, v36, v56, v118
	v_fma_f32 v59, v36, v57, v119
	v_fma_f32 v54, -v37, v57, v58
	v_fma_f32 v55, v37, v56, v59
	v_cvt_pk_bf16_f32 v62, v54, v55
	ds_write_b16 v60, v62 offset:816
	ds_write_b16_d16_hi v60, v62 offset:944
	s_waitcnt lgkmcnt(15)
	v_fma_f32 v58, v36, v54, v120
	v_fma_f32 v59, v36, v55, v121
	v_fma_f32 v56, -v37, v55, v58
	v_fma_f32 v57, v37, v54, v59
	v_cvt_pk_bf16_f32 v62, v56, v57
	ds_write_b16 v60, v62 offset:1088
	ds_write_b16_d16_hi v60, v62 offset:1216
	s_waitcnt lgkmcnt(15)
	v_fma_f32 v58, v36, v56, v122
	v_fma_f32 v59, v36, v57, v123
	v_fma_f32 v54, -v37, v57, v58
	v_fma_f32 v55, v37, v56, v59
	v_cvt_pk_bf16_f32 v62, v54, v55
	ds_write_b16 v60, v62 offset:1360
	ds_write_b16_d16_hi v60, v62 offset:1488
	s_waitcnt lgkmcnt(15)
	v_fma_f32 v58, v36, v54, v124
	v_fma_f32 v59, v36, v55, v125
	v_fma_f32 v56, -v37, v55, v58
	v_fma_f32 v57, v37, v54, v59
	v_cvt_pk_bf16_f32 v62, v56, v57
	ds_write_b16 v60, v62 offset:1632
	ds_write_b16_d16_hi v60, v62 offset:1760
	s_waitcnt lgkmcnt(15)
; __device__ void phase_s5_pass2(CParams& p, int l, int item, char* smem) {
;     ...
;   for (int dir = 0; dir < 2; dir++) {
;     int pidx = ((l * 2 + dir) * 16 + g) * 64 + lane;
;     float2 A = p.Apar[pidx];
;     f32x2 bb[16];
; #pragma unroll
;     for (int cc = 0; cc < 16; cc++) {
;       float2 b = p.Bbar[(size_t)pidx * 16 + cc];
;       bb[cc] = f32x2{b.x, b.y};
;     }
;     bf16x8 cf[4];
; #pragma unroll
;     for (int ks = 0; ks < 4; ks++) {
;       int k = ks * 32 + lq * 8;
;       bool im = k >= 64;
;       const float* src = (im ? p.c_im : p.c_re) + ((((size_t)(l * 2 + dir) * 16 + g) * 16 + l15) * 64) + (k & 63);
;       float4 v0 = *(const float4*)src, v1 = *(const float4*)(src + 4);
;       float sgn = im ? -1.f : 1.f;
;       cf[ks][0] = (short)f2bf(sgn * v0.x); cf[ks][1] = (short)f2bf(sgn * v0.y);
;       cf[ks][2] = (short)f2bf(sgn * v0.z); cf[ks][3] = (short)f2bf(sgn * v0.w);
;       cf[ks][4] = (short)f2bf(sgn * v1.x); cf[ks][5] = (short)f2bf(sgn * v1.y);
;       cf[ks][6] = (short)f2bf(sgn * v1.z); cf[ks][7] = (short)f2bf(sgn * v1.w);
;     }
;     float2 h0 = p.Hin[(((size_t)q * 2 + dir) * 16 + g) * 64 + lane];
;     float hr = h0.x, hi = h0.y;
;     ...
;     for (int s = 0; s < 4; s++) {
;       const int sb = dir == 0 ? s : 3 - s;
;       for (int i = 0; i < 16; i++) {
;         int tl = dir == 0 ? i : 15 - i;
;         int t = sb * 16 + tl;
;         float u[16];
; #pragma unroll
;         for (int k = 0; k < 4; k++) {
;           float4 uv = *(const float4*)(us + t * 16 + k * 4);
;           u[k * 4] = uv.x; u[k * 4 + 1] = uv.y; u[k * 4 + 2] = uv.z; u[k * 4 + 3] = uv.w;
;         }
;         f32x2 bu = {0.f, 0.f};
; #pragma unroll
;         for (int cc = 0; cc < 16; cc++) bu = __builtin_elementwise_fma(bb[cc], f32x2{u[cc], u[cc]}, bu);
;         float nr = A.x * hr - A.y * hi + bu[0];
;         float ni = A.x * hi + A.y * hr + bu[1];
;         hr = nr; hi = ni;
;         hs[tl * 136 + lane] = f2bf(hr);
;         hs[tl * 136 + 64 + lane] = f2bf(hi);
;       }
;       __syncthreads();
; #pragma unroll
;       for (int ks = 0; ks < 4; ks++) {
;         bf16x8 a = *(const bf16x8*)(hs + l15 * 136 + ks * 32 + lq * 8);
;         acc[sb] = __builtin_amdgcn_mfma_f32_16x16x32_bf16(a, cf[ks], acc[sb], 0, 0, 0);
;       }
	v_fma_f32 v58, v36, v56, v126
	v_fma_f32 v59, v36, v57, v127
	v_fma_f32 v54, -v37, v57, v58
	v_fma_f32 v55, v37, v56, v59
	v_cvt_pk_bf16_f32 v62, v54, v55
	ds_write_b16 v60, v62 offset:1904
	ds_write_b16_d16_hi v60, v62 offset:2032
	s_waitcnt lgkmcnt(15)
	v_fma_f32 v58, v36, v54, v128
	v_fma_f32 v59, v36, v55, v129
	v_fma_f32 v56, -v37, v55, v58
	v_fma_f32 v57, v37, v54, v59
	v_cvt_pk_bf16_f32 v62, v56, v57
	ds_write_b16 v60, v62 offset:2176
	ds_write_b16_d16_hi v60, v62 offset:2304
	s_waitcnt lgkmcnt(15)
	v_fma_f32 v58, v36, v56, v130
	v_fma_f32 v59, v36, v57, v131
	v_fma_f32 v54, -v37, v57, v58
	v_fma_f32 v55, v37, v56, v59
	v_cvt_pk_bf16_f32 v62, v54, v55
	ds_write_b16 v60, v62 offset:2448
	ds_write_b16_d16_hi v60, v62 offset:2576
	s_waitcnt lgkmcnt(15)
	v_fma_f32 v58, v36, v54, v132
	v_fma_f32 v59, v36, v55, v133
	v_fma_f32 v56, -v37, v55, v58
	v_fma_f32 v57, v37, v54, v59
	v_cvt_pk_bf16_f32 v62, v56, v57
	ds_write_b16 v60, v62 offset:2720
	ds_write_b16_d16_hi v60, v62 offset:2848
	s_waitcnt lgkmcnt(15)
	v_fma_f32 v58, v36, v56, v134
	v_fma_f32 v59, v36, v57, v135
	v_fma_f32 v54, -v37, v57, v58
	v_fma_f32 v55, v37, v56, v59
	v_cvt_pk_bf16_f32 v62, v54, v55
	ds_write_b16 v60, v62 offset:2992
	ds_write_b16_d16_hi v60, v62 offset:3120
	s_waitcnt lgkmcnt(15)
	v_fma_f32 v58, v36, v54, v136
	v_fma_f32 v59, v36, v55, v137
	v_fma_f32 v56, -v37, v55, v58
	v_fma_f32 v57, v37, v54, v59
	v_cvt_pk_bf16_f32 v62, v56, v57
	ds_write_b16 v60, v62 offset:3264
	ds_write_b16_d16_hi v60, v62 offset:3392
	s_waitcnt lgkmcnt(15)
	v_fma_f32 v58, v36, v56, v138
	v_fma_f32 v59, v36, v57, v139
	v_fma_f32 v54, -v37, v57, v58
	v_fma_f32 v55, v37, v56, v59
	v_cvt_pk_bf16_f32 v62, v54, v55
	ds_write_b16 v60, v62 offset:3536
	ds_write_b16_d16_hi v60, v62 offset:3664
	s_waitcnt lgkmcnt(15)
	v_fma_f32 v58, v36, v54, v140
	v_fma_f32 v59, v36, v55, v141
	v_fma_f32 v56, -v37, v55, v58
	v_fma_f32 v57, v37, v54, v59
	v_cvt_pk_bf16_f32 v62, v56, v57
	ds_write_b16 v60, v62 offset:3808
	ds_write_b16_d16_hi v60, v62 offset:3936
	s_waitcnt lgkmcnt(15)
	v_fma_f32 v58, v36, v56, v142
	v_fma_f32 v59, v36, v57, v143
	v_fma_f32 v54, -v37, v57, v58
	v_fma_f32 v55, v37, v56, v59
	v_cvt_pk_bf16_f32 v62, v54, v55
	ds_write_b16 v60, v62 offset:4080
	ds_write_b16_d16_hi v60, v62 offset:4208
	ds_read_b128 v[184:187], v61 offset:0
	ds_read_b128 v[188:191], v61 offset:64
	ds_read_b128 v[192:195], v61 offset:128
	ds_read_b128 v[196:199], v61 offset:192
	s_waitcnt lgkmcnt(0)
	v_mfma_f32_16x16x32_bf16 v[160:163], v[184:187], v[168:171], v[160:163]
	v_mfma_f32_16x16x32_bf16 v[160:163], v[188:191], v[172:175], v[160:163]
	v_mfma_f32_16x16x32_bf16 v[160:163], v[192:195], v[176:179], v[160:163]
	v_mfma_f32_16x16x32_bf16 v[160:163], v[196:199], v[180:183], v[160:163]
	s_lshl_b32 s20, s12, 1
	s_add_u32 s20, s20, 1
	s_lshl_b32 s20, s20, 4
	s_add_u32 s20, s20, s2
	s_lshl_b32 s19, s20, 6
	s_load_dwordx2 s[22:23], s[44:45], 0x168
	s_load_dwordx2 s[24:25], s[44:45], 0x170
	s_load_dwordx2 s[26:27], s[44:45], 0x68
	s_load_dwordx2 s[34:35], s[44:45], 0x70
	s_load_dwordx2 s[40:41], s[44:45], 0x180
	s_waitcnt lgkmcnt(0)
	s_lshl_b32 s20, s19, 3
	s_add_u32 s22, s22, s20
	s_addc_u32 s23, s23, 0
	s_lshl_b32 s20, s19, 7
	s_add_u32 s24, s24, s20
	s_addc_u32 s25, s25, 0
	s_lshl_b32 s20, s19, 6
	s_add_u32 s26, s26, s20
	s_addc_u32 s27, s27, 0
	s_add_u32 s34, s34, s20
	s_addc_u32 s35, s35, 0
	s_lshl_b32 s20, s1, 1
	s_add_u32 s20, s20, 1
	s_lshl_b32 s20, s20, 4
	s_add_u32 s20, s20, s2
	s_lshl_b32 s20, s20, 9
	s_add_u32 s40, s40, s20
	s_addc_u32 s41, s41, 0
	v_lshlrev_b32_e32 v38, 3, v32
	global_load_dwordx2 v[36:37], v38, s[22:23]
	global_load_dwordx2 v[54:55], v38, s[40:41]
	global_load_dwordx2 v[64:65], v40, s[24:25] offset:0
	global_load_dwordx2 v[66:67], v40, s[24:25] offset:8
	global_load_dwordx2 v[68:69], v40, s[24:25] offset:16
	global_load_dwordx2 v[70:71], v40, s[24:25] offset:24
	global_load_dwordx2 v[72:73], v40, s[24:25] offset:2048
	global_load_dwordx2 v[74:75], v40, s[24:25] offset:2056
	global_load_dwordx2 v[76:77], v40, s[24:25] offset:2064
	global_load_dwordx2 v[78:79], v40, s[24:25] offset:2072
	global_load_dwordx2 v[80:81], v41, s[24:25] offset:0
	global_load_dwordx2 v[82:83], v41, s[24:25] offset:8
	global_load_dwordx2 v[84:85], v41, s[24:25] offset:16
	global_load_dwordx2 v[86:87], v41, s[24:25] offset:24
	global_load_dwordx2 v[88:89], v41, s[24:25] offset:2048
	global_load_dwordx2 v[90:91], v41, s[24:25] offset:2056
	global_load_dwordx2 v[92:93], v41, s[24:25] offset:2064
	global_load_dwordx2 v[94:95], v41, s[24:25] offset:2072
	global_load_dwordx4 v[112:115], v49, s[26:27] offset:0
	global_load_dwordx4 v[116:119], v49, s[26:27] offset:16
	global_load_dwordx4 v[120:123], v49, s[26:27] offset:128
	global_load_dwordx4 v[124:127], v49, s[26:27] offset:144
	global_load_dwordx4 v[128:131], v49, s[34:35] offset:0
	global_load_dwordx4 v[132:135], v49, s[34:35] offset:16
	global_load_dwordx4 v[136:139], v49, s[34:35] offset:128
	global_load_dwordx4 v[140:143], v49, s[34:35] offset:144
	v_sub_u32_e32 v38, 63, v33
	v_lshlrev_b32_e32 v42, 10, v38
	v_lshl_add_u32 v42, v34, 4, v42
	s_mov_b32 s98, 0xffffc000
	global_load_dwordx4 v[96:99], v42, s[6:7]
	v_add_u32_e32 v42, s98, v42
	global_load_dwordx4 v[100:103], v42, s[6:7]
	v_add_u32_e32 v42, s98, v42
	global_load_dwordx4 v[104:107], v42, s[6:7]
	v_add_u32_e32 v42, s98, v42
	global_load_dwordx4 v[108:111], v42, s[6:7]
	s_waitcnt vmcnt(4)
; __device__ void phase_s5_pass2(CParams& p, int l, int item, char* smem) {
;     ...
;     for (int ks = 0; ks < 4; ks++) {
;       int k = ks * 32 + lq * 8;
;       bool im = k >= 64;
;       const float* src = (im ? p.c_im : p.c_re) + ((((size_t)(l * 2 + dir) * 16 + g) * 16 + l15) * 64) + (k & 63);
;       float4 v0 = *(const float4*)src, v1 = *(const float4*)(src + 4);
;       float sgn = im ? -1.f : 1.f;
;       cf[ks][0] = (short)f2bf(sgn * v0.x); cf[ks][1] = (short)f2bf(sgn * v0.y);
;       cf[ks][2] = (short)f2bf(sgn * v0.z); cf[ks][3] = (short)f2bf(sgn * v0.w);
;       cf[ks][4] = (short)f2bf(sgn * v1.x); cf[ks][5] = (short)f2bf(sgn * v1.y);
;       cf[ks][6] = (short)f2bf(sgn * v1.z); cf[ks][7] = (short)f2bf(sgn * v1.w);
;     }
;     ...
;     for (int s = 0; s < 4; s++) {
;       const int sb = dir == 0 ? s : 3 - s;
;       for (int i = 0; i < 16; i++) {
;         int tl = dir == 0 ? i : 15 - i;
;         int t = sb * 16 + tl;
;         float u[16];
; #pragma unroll
;         for (int k = 0; k < 4; k++) {
;           float4 uv = *(const float4*)(us + t * 16 + k * 4);
;           u[k * 4] = uv.x; u[k * 4 + 1] = uv.y; u[k * 4 + 2] = uv.z; u[k * 4 + 3] = uv.w;
;         }
;         f32x2 bu = {0.f, 0.f};
; #pragma unroll
;         for (int cc = 0; cc < 16; cc++) bu = __builtin_elementwise_fma(bb[cc], f32x2{u[cc], u[cc]}, bu);
;         float nr = A.x * hr - A.y * hi + bu[0];
;         float ni = A.x * hi + A.y * hr + bu[1];
;         hr = nr; hi = ni;
;         hs[tl * 136 + lane] = f2bf(hr);
;         hs[tl * 136 + 64 + lane] = f2bf(hi);
;       }
	v_cvt_pk_bf16_f32 v168, v112, v113
	v_cvt_pk_bf16_f32 v169, v114, v115
	v_cvt_pk_bf16_f32 v170, v116, v117
	v_cvt_pk_bf16_f32 v171, v118, v119
	v_cvt_pk_bf16_f32 v172, v120, v121
	v_cvt_pk_bf16_f32 v173, v122, v123
	v_cvt_pk_bf16_f32 v174, v124, v125
	v_cvt_pk_bf16_f32 v175, v126, v127
	v_cvt_pk_bf16_f32 v176, v128, v129
	v_xor_b32_e32 v176, 0x80008000, v176
	v_cvt_pk_bf16_f32 v177, v130, v131
	v_xor_b32_e32 v177, 0x80008000, v177
	v_cvt_pk_bf16_f32 v178, v132, v133
	v_xor_b32_e32 v178, 0x80008000, v178
	v_cvt_pk_bf16_f32 v179, v134, v135
	v_xor_b32_e32 v179, 0x80008000, v179
	v_cvt_pk_bf16_f32 v180, v136, v137
	v_xor_b32_e32 v180, 0x80008000, v180
	v_cvt_pk_bf16_f32 v181, v138, v139
	v_xor_b32_e32 v181, 0x80008000, v181
	v_cvt_pk_bf16_f32 v182, v140, v141
	v_xor_b32_e32 v182, 0x80008000, v182
	v_cvt_pk_bf16_f32 v183, v142, v143
	v_xor_b32_e32 v183, 0x80008000, v183
	s_waitcnt vmcnt(3)
	v_mfma_f32_16x16x4_f32 v[0:3], v96, v64, 0
	v_mfma_f32_16x16x4_f32 v[4:7], v96, v65, 0
	v_mfma_f32_16x16x4_f32 v[8:11], v96, v72, 0
	v_mfma_f32_16x16x4_f32 v[12:15], v96, v73, 0
	v_mfma_f32_16x16x4_f32 v[16:19], v96, v80, 0
	v_mfma_f32_16x16x4_f32 v[20:23], v96, v81, 0
	v_mfma_f32_16x16x4_f32 v[24:27], v96, v88, 0
	v_mfma_f32_16x16x4_f32 v[28:31], v96, v89, 0
	v_mfma_f32_16x16x4_f32 v[0:3], v97, v66, v[0:3]
	v_mfma_f32_16x16x4_f32 v[4:7], v97, v67, v[4:7]
	v_mfma_f32_16x16x4_f32 v[8:11], v97, v74, v[8:11]
	v_mfma_f32_16x16x4_f32 v[12:15], v97, v75, v[12:15]
	v_mfma_f32_16x16x4_f32 v[16:19], v97, v82, v[16:19]
	v_mfma_f32_16x16x4_f32 v[20:23], v97, v83, v[20:23]
	v_mfma_f32_16x16x4_f32 v[24:27], v97, v90, v[24:27]
	v_mfma_f32_16x16x4_f32 v[28:31], v97, v91, v[28:31]
	v_mfma_f32_16x16x4_f32 v[0:3], v98, v68, v[0:3]
	v_mfma_f32_16x16x4_f32 v[4:7], v98, v69, v[4:7]
	v_mfma_f32_16x16x4_f32 v[8:11], v98, v76, v[8:11]
	v_mfma_f32_16x16x4_f32 v[12:15], v98, v77, v[12:15]
	v_mfma_f32_16x16x4_f32 v[16:19], v98, v84, v[16:19]
	v_mfma_f32_16x16x4_f32 v[20:23], v98, v85, v[20:23]
	v_mfma_f32_16x16x4_f32 v[24:27], v98, v92, v[24:27]
	v_mfma_f32_16x16x4_f32 v[28:31], v98, v93, v[28:31]
	v_mfma_f32_16x16x4_f32 v[0:3], v99, v70, v[0:3]
	v_mfma_f32_16x16x4_f32 v[4:7], v99, v71, v[4:7]
	v_mfma_f32_16x16x4_f32 v[8:11], v99, v78, v[8:11]
	v_mfma_f32_16x16x4_f32 v[12:15], v99, v79, v[12:15]
	v_mfma_f32_16x16x4_f32 v[16:19], v99, v86, v[16:19]
	v_mfma_f32_16x16x4_f32 v[20:23], v99, v87, v[20:23]
	v_mfma_f32_16x16x4_f32 v[24:27], v99, v94, v[24:27]
	v_mfma_f32_16x16x4_f32 v[28:31], v99, v95, v[28:31]
	s_nop 15
	s_nop 15
	ds_write2_b32 v44, v0, v4 offset0:0 offset1:1
	ds_write2_b32 v45, v1, v5 offset0:0 offset1:1
	ds_write2_b32 v46, v2, v6 offset0:0 offset1:1
	ds_write2_b32 v47, v3, v7 offset0:0 offset1:1
	ds_write2_b32 v44, v8, v12 offset0:32 offset1:33
	ds_write2_b32 v45, v9, v13 offset0:32 offset1:33
	ds_write2_b32 v46, v10, v14 offset0:32 offset1:33
	ds_write2_b32 v47, v11, v15 offset0:32 offset1:33
	ds_write2_b32 v44, v16, v20 offset0:64 offset1:65
	ds_write2_b32 v45, v17, v21 offset0:64 offset1:65
	ds_write2_b32 v46, v18, v22 offset0:64 offset1:65
	ds_write2_b32 v47, v19, v23 offset0:64 offset1:65
	ds_write2_b32 v44, v24, v28 offset0:96 offset1:97
	ds_write2_b32 v45, v25, v29 offset0:96 offset1:97
	ds_write2_b32 v46, v26, v30 offset0:96 offset1:97
	ds_write2_b32 v47, v27, v31 offset0:96 offset1:97
	ds_read_b64 v[0:1], v52 offset:0
	ds_read_b64 v[2:3], v52 offset:512
	ds_read_b64 v[4:5], v52 offset:1024
	ds_read_b64 v[6:7], v52 offset:1536
	ds_read_b64 v[8:9], v52 offset:2048
	ds_read_b64 v[10:11], v52 offset:2560
	ds_read_b64 v[12:13], v52 offset:3072
	ds_read_b64 v[14:15], v52 offset:3584
	ds_read_b64 v[16:17], v52 offset:4096
	ds_read_b64 v[18:19], v52 offset:4608
	ds_read_b64 v[20:21], v52 offset:5120
	ds_read_b64 v[22:23], v52 offset:5632
	ds_read_b64 v[24:25], v52 offset:6144
	ds_read_b64 v[26:27], v52 offset:6656
	ds_read_b64 v[28:29], v52 offset:7168
	ds_read_b64 v[30:31], v52 offset:7680
	s_waitcnt vmcnt(2)
	s_waitcnt lgkmcnt(15)
	v_fma_f32 v58, v36, v54, v0
	v_fma_f32 v59, v36, v55, v1
	v_mfma_f32_16x16x4_f32 v[112:115], v100, v64, 0
	v_mfma_f32_16x16x4_f32 v[116:119], v100, v65, 0
	v_fma_f32 v56, -v37, v55, v58
	v_fma_f32 v57, v37, v54, v59
	v_cvt_pk_bf16_f32 v62, v56, v57
	ds_write_b16 v60, v62 offset:4080
	ds_write_b16_d16_hi v60, v62 offset:4208
	s_waitcnt lgkmcnt(15)
	v_fma_f32 v58, v36, v56, v2
	v_fma_f32 v59, v36, v57, v3
	v_mfma_f32_16x16x4_f32 v[120:123], v100, v72, 0
	v_mfma_f32_16x16x4_f32 v[124:127], v100, v73, 0
	v_fma_f32 v54, -v37, v57, v58
	v_fma_f32 v55, v37, v56, v59
	v_cvt_pk_bf16_f32 v62, v54, v55
	ds_write_b16 v60, v62 offset:3808
	ds_write_b16_d16_hi v60, v62 offset:3936
	s_waitcnt lgkmcnt(15)
	v_fma_f32 v58, v36, v54, v4
	v_fma_f32 v59, v36, v55, v5
	v_mfma_f32_16x16x4_f32 v[128:131], v100, v80, 0
	v_mfma_f32_16x16x4_f32 v[132:135], v100, v81, 0
	v_fma_f32 v56, -v37, v55, v58
	v_fma_f32 v57, v37, v54, v59
	v_cvt_pk_bf16_f32 v62, v56, v57
	ds_write_b16 v60, v62 offset:3536
	ds_write_b16_d16_hi v60, v62 offset:3664
	s_waitcnt lgkmcnt(15)
	v_fma_f32 v58, v36, v56, v6
	v_fma_f32 v59, v36, v57, v7
	v_mfma_f32_16x16x4_f32 v[136:139], v100, v88, 0
	v_mfma_f32_16x16x4_f32 v[140:143], v100, v89, 0
	v_fma_f32 v54, -v37, v57, v58
	v_fma_f32 v55, v37, v56, v59
	v_cvt_pk_bf16_f32 v62, v54, v55
	ds_write_b16 v60, v62 offset:3264
	ds_write_b16_d16_hi v60, v62 offset:3392
	s_waitcnt lgkmcnt(15)
	v_fma_f32 v58, v36, v54, v8
	v_fma_f32 v59, v36, v55, v9
	v_mfma_f32_16x16x4_f32 v[112:115], v101, v66, v[112:115]
	v_mfma_f32_16x16x4_f32 v[116:119], v101, v67, v[116:119]
	v_fma_f32 v56, -v37, v55, v58
	v_fma_f32 v57, v37, v54, v59
	v_cvt_pk_bf16_f32 v62, v56, v57
	ds_write_b16 v60, v62 offset:2992
	ds_write_b16_d16_hi v60, v62 offset:3120
	s_waitcnt lgkmcnt(15)
; __device__ void phase_s5_pass2(CParams& p, int l, int item, char* smem) {
;     ...
;     for (int s = 0; s < 4; s++) {
;       const int sb = dir == 0 ? s : 3 - s;
;       for (int i = 0; i < 16; i++) {
;         int tl = dir == 0 ? i : 15 - i;
;         int t = sb * 16 + tl;
;         float u[16];
; #pragma unroll
;         for (int k = 0; k < 4; k++) {
;           float4 uv = *(const float4*)(us + t * 16 + k * 4);
;           u[k * 4] = uv.x; u[k * 4 + 1] = uv.y; u[k * 4 + 2] = uv.z; u[k * 4 + 3] = uv.w;
;         }
;         f32x2 bu = {0.f, 0.f};
; #pragma unroll
;         for (int cc = 0; cc < 16; cc++) bu = __builtin_elementwise_fma(bb[cc], f32x2{u[cc], u[cc]}, bu);
;         float nr = A.x * hr - A.y * hi + bu[0];
;         float ni = A.x * hi + A.y * hr + bu[1];
;         hr = nr; hi = ni;
;         hs[tl * 136 + lane] = f2bf(hr);
;         hs[tl * 136 + 64 + lane] = f2bf(hi);
;       }
;       __syncthreads();
; #pragma unroll
;       for (int ks = 0; ks < 4; ks++) {
;         bf16x8 a = *(const bf16x8*)(hs + l15 * 136 + ks * 32 + lq * 8);
;         acc[sb] = __builtin_amdgcn_mfma_f32_16x16x32_bf16(a, cf[ks], acc[sb], 0, 0, 0);
;       }
	v_fma_f32 v58, v36, v56, v10
	v_fma_f32 v59, v36, v57, v11
	v_mfma_f32_16x16x4_f32 v[120:123], v101, v74, v[120:123]
	v_mfma_f32_16x16x4_f32 v[124:127], v101, v75, v[124:127]
	v_fma_f32 v54, -v37, v57, v58
	v_fma_f32 v55, v37, v56, v59
	v_cvt_pk_bf16_f32 v62, v54, v55
	ds_write_b16 v60, v62 offset:2720
	ds_write_b16_d16_hi v60, v62 offset:2848
	s_waitcnt lgkmcnt(15)
	v_fma_f32 v58, v36, v54, v12
	v_fma_f32 v59, v36, v55, v13
	v_mfma_f32_16x16x4_f32 v[128:131], v101, v82, v[128:131]
	v_mfma_f32_16x16x4_f32 v[132:135], v101, v83, v[132:135]
	v_fma_f32 v56, -v37, v55, v58
	v_fma_f32 v57, v37, v54, v59
	v_cvt_pk_bf16_f32 v62, v56, v57
	ds_write_b16 v60, v62 offset:2448
	ds_write_b16_d16_hi v60, v62 offset:2576
	s_waitcnt lgkmcnt(15)
	v_fma_f32 v58, v36, v56, v14
	v_fma_f32 v59, v36, v57, v15
	v_mfma_f32_16x16x4_f32 v[136:139], v101, v90, v[136:139]
	v_mfma_f32_16x16x4_f32 v[140:143], v101, v91, v[140:143]
	v_fma_f32 v54, -v37, v57, v58
	v_fma_f32 v55, v37, v56, v59
	v_cvt_pk_bf16_f32 v62, v54, v55
	ds_write_b16 v60, v62 offset:2176
	ds_write_b16_d16_hi v60, v62 offset:2304
	s_waitcnt lgkmcnt(15)
	v_fma_f32 v58, v36, v54, v16
	v_fma_f32 v59, v36, v55, v17
	v_mfma_f32_16x16x4_f32 v[112:115], v102, v68, v[112:115]
	v_mfma_f32_16x16x4_f32 v[116:119], v102, v69, v[116:119]
	v_fma_f32 v56, -v37, v55, v58
	v_fma_f32 v57, v37, v54, v59
	v_cvt_pk_bf16_f32 v62, v56, v57
	ds_write_b16 v60, v62 offset:1904
	ds_write_b16_d16_hi v60, v62 offset:2032
	s_waitcnt lgkmcnt(15)
	v_fma_f32 v58, v36, v56, v18
	v_fma_f32 v59, v36, v57, v19
	v_mfma_f32_16x16x4_f32 v[120:123], v102, v76, v[120:123]
	v_mfma_f32_16x16x4_f32 v[124:127], v102, v77, v[124:127]
	v_fma_f32 v54, -v37, v57, v58
	v_fma_f32 v55, v37, v56, v59
	v_cvt_pk_bf16_f32 v62, v54, v55
	ds_write_b16 v60, v62 offset:1632
	ds_write_b16_d16_hi v60, v62 offset:1760
	s_waitcnt lgkmcnt(15)
	v_fma_f32 v58, v36, v54, v20
	v_fma_f32 v59, v36, v55, v21
	v_mfma_f32_16x16x4_f32 v[128:131], v102, v84, v[128:131]
	v_mfma_f32_16x16x4_f32 v[132:135], v102, v85, v[132:135]
	v_fma_f32 v56, -v37, v55, v58
	v_fma_f32 v57, v37, v54, v59
	v_cvt_pk_bf16_f32 v62, v56, v57
	ds_write_b16 v60, v62 offset:1360
	ds_write_b16_d16_hi v60, v62 offset:1488
	s_waitcnt lgkmcnt(15)
	v_fma_f32 v58, v36, v56, v22
	v_fma_f32 v59, v36, v57, v23
	v_mfma_f32_16x16x4_f32 v[136:139], v102, v92, v[136:139]
	v_mfma_f32_16x16x4_f32 v[140:143], v102, v93, v[140:143]
	v_fma_f32 v54, -v37, v57, v58
	v_fma_f32 v55, v37, v56, v59
	v_cvt_pk_bf16_f32 v62, v54, v55
	ds_write_b16 v60, v62 offset:1088
	ds_write_b16_d16_hi v60, v62 offset:1216
	s_waitcnt lgkmcnt(15)
	v_fma_f32 v58, v36, v54, v24
	v_fma_f32 v59, v36, v55, v25
	v_mfma_f32_16x16x4_f32 v[112:115], v103, v70, v[112:115]
	v_mfma_f32_16x16x4_f32 v[116:119], v103, v71, v[116:119]
	v_fma_f32 v56, -v37, v55, v58
	v_fma_f32 v57, v37, v54, v59
	v_cvt_pk_bf16_f32 v62, v56, v57
	ds_write_b16 v60, v62 offset:816
	ds_write_b16_d16_hi v60, v62 offset:944
	s_waitcnt lgkmcnt(15)
	v_fma_f32 v58, v36, v56, v26
	v_fma_f32 v59, v36, v57, v27
	v_mfma_f32_16x16x4_f32 v[120:123], v103, v78, v[120:123]
	v_mfma_f32_16x16x4_f32 v[124:127], v103, v79, v[124:127]
	v_fma_f32 v54, -v37, v57, v58
	v_fma_f32 v55, v37, v56, v59
	v_cvt_pk_bf16_f32 v62, v54, v55
	ds_write_b16 v60, v62 offset:544
	ds_write_b16_d16_hi v60, v62 offset:672
	s_waitcnt lgkmcnt(15)
	v_fma_f32 v58, v36, v54, v28
	v_fma_f32 v59, v36, v55, v29
	v_mfma_f32_16x16x4_f32 v[128:131], v103, v86, v[128:131]
	v_mfma_f32_16x16x4_f32 v[132:135], v103, v87, v[132:135]
	v_fma_f32 v56, -v37, v55, v58
	v_fma_f32 v57, v37, v54, v59
	v_cvt_pk_bf16_f32 v62, v56, v57
	ds_write_b16 v60, v62 offset:272
	ds_write_b16_d16_hi v60, v62 offset:400
	s_waitcnt lgkmcnt(15)
	v_fma_f32 v58, v36, v56, v30
	v_fma_f32 v59, v36, v57, v31
	v_mfma_f32_16x16x4_f32 v[136:139], v103, v94, v[136:139]
	v_mfma_f32_16x16x4_f32 v[140:143], v103, v95, v[140:143]
	v_fma_f32 v54, -v37, v57, v58
	v_fma_f32 v55, v37, v56, v59
	v_cvt_pk_bf16_f32 v62, v54, v55
	ds_write_b16 v60, v62 offset:0
	ds_write_b16_d16_hi v60, v62 offset:128
	ds_read_b128 v[184:187], v61 offset:0
	ds_read_b128 v[188:191], v61 offset:64
	ds_read_b128 v[192:195], v61 offset:128
	ds_read_b128 v[196:199], v61 offset:192
	s_waitcnt lgkmcnt(0)
	v_mfma_f32_16x16x32_bf16 v[160:163], v[184:187], v[168:171], v[160:163]
	v_mfma_f32_16x16x32_bf16 v[160:163], v[188:191], v[172:175], v[160:163]
	v_mfma_f32_16x16x32_bf16 v[160:163], v[192:195], v[176:179], v[160:163]
	v_mfma_f32_16x16x32_bf16 v[160:163], v[196:199], v[180:183], v[160:163]
	s_nop 15
	s_nop 15
	ds_write2_b32 v44, v112, v116 offset0:0 offset1:1
	ds_write2_b32 v45, v113, v117 offset0:0 offset1:1
	ds_write2_b32 v46, v114, v118 offset0:0 offset1:1
	ds_write2_b32 v47, v115, v119 offset0:0 offset1:1
	ds_write2_b32 v44, v120, v124 offset0:32 offset1:33
	ds_write2_b32 v45, v121, v125 offset0:32 offset1:33
	ds_write2_b32 v46, v122, v126 offset0:32 offset1:33
	ds_write2_b32 v47, v123, v127 offset0:32 offset1:33
	ds_write2_b32 v44, v128, v132 offset0:64 offset1:65
	ds_write2_b32 v45, v129, v133 offset0:64 offset1:65
	ds_write2_b32 v46, v130, v134 offset0:64 offset1:65
	ds_write2_b32 v47, v131, v135 offset0:64 offset1:65
	ds_write2_b32 v44, v136, v140 offset0:96 offset1:97
	ds_write2_b32 v45, v137, v141 offset0:96 offset1:97
	ds_write2_b32 v46, v138, v142 offset0:96 offset1:97
	ds_write2_b32 v47, v139, v143 offset0:96 offset1:97
	ds_read_b64 v[112:113], v52 offset:0
	ds_read_b64 v[114:115], v52 offset:512
	ds_read_b64 v[116:117], v52 offset:1024
	ds_read_b64 v[118:119], v52 offset:1536
	ds_read_b64 v[120:121], v52 offset:2048
	ds_read_b64 v[122:123], v52 offset:2560
	ds_read_b64 v[124:125], v52 offset:3072
	ds_read_b64 v[126:127], v52 offset:3584
	ds_read_b64 v[128:129], v52 offset:4096
	ds_read_b64 v[130:131], v52 offset:4608
	ds_read_b64 v[132:133], v52 offset:5120
	ds_read_b64 v[134:135], v52 offset:5632
	ds_read_b64 v[136:137], v52 offset:6144
	ds_read_b64 v[138:139], v52 offset:6656
	ds_read_b64 v[140:141], v52 offset:7168
	ds_read_b64 v[142:143], v52 offset:7680
	s_waitcnt vmcnt(1)
; __device__ void phase_s5_pass2(CParams& p, int l, int item, char* smem) {
;     ...
;     for (int s = 0; s < 4; s++) {
;       const int sb = dir == 0 ? s : 3 - s;
;       for (int i = 0; i < 16; i++) {
;         int tl = dir == 0 ? i : 15 - i;
;         int t = sb * 16 + tl;
;         float u[16];
; #pragma unroll
;         for (int k = 0; k < 4; k++) {
;           float4 uv = *(const float4*)(us + t * 16 + k * 4);
;           u[k * 4] = uv.x; u[k * 4 + 1] = uv.y; u[k * 4 + 2] = uv.z; u[k * 4 + 3] = uv.w;
;         }
;         f32x2 bu = {0.f, 0.f};
; #pragma unroll
;         for (int cc = 0; cc < 16; cc++) bu = __builtin_elementwise_fma(bb[cc], f32x2{u[cc], u[cc]}, bu);
;         float nr = A.x * hr - A.y * hi + bu[0];
;         float ni = A.x * hi + A.y * hr + bu[1];
;         hr = nr; hi = ni;
;         hs[tl * 136 + lane] = f2bf(hr);
;         hs[tl * 136 + 64 + lane] = f2bf(hi);
;       }
;       __syncthreads();
; #pragma unroll
;       for (int ks = 0; ks < 4; ks++) {
;         bf16x8 a = *(const bf16x8*)(hs + l15 * 136 + ks * 32 + lq * 8);
;         acc[sb] = __builtin_amdgcn_mfma_f32_16x16x32_bf16(a, cf[ks], acc[sb], 0, 0, 0);
;       }
	s_waitcnt lgkmcnt(15)
	v_fma_f32 v58, v36, v54, v112
	v_fma_f32 v59, v36, v55, v113
	v_mfma_f32_16x16x4_f32 v[0:3], v104, v64, 0
	v_mfma_f32_16x16x4_f32 v[4:7], v104, v65, 0
	v_fma_f32 v56, -v37, v55, v58
	v_fma_f32 v57, v37, v54, v59
	v_cvt_pk_bf16_f32 v62, v56, v57
	ds_write_b16 v60, v62 offset:4080
	ds_write_b16_d16_hi v60, v62 offset:4208
	s_waitcnt lgkmcnt(15)
	v_fma_f32 v58, v36, v56, v114
	v_fma_f32 v59, v36, v57, v115
	v_mfma_f32_16x16x4_f32 v[8:11], v104, v72, 0
	v_mfma_f32_16x16x4_f32 v[12:15], v104, v73, 0
	v_fma_f32 v54, -v37, v57, v58
	v_fma_f32 v55, v37, v56, v59
	v_cvt_pk_bf16_f32 v62, v54, v55
	ds_write_b16 v60, v62 offset:3808
	ds_write_b16_d16_hi v60, v62 offset:3936
	s_waitcnt lgkmcnt(15)
	v_fma_f32 v58, v36, v54, v116
	v_fma_f32 v59, v36, v55, v117
	v_mfma_f32_16x16x4_f32 v[16:19], v104, v80, 0
	v_mfma_f32_16x16x4_f32 v[20:23], v104, v81, 0
	v_fma_f32 v56, -v37, v55, v58
	v_fma_f32 v57, v37, v54, v59
	v_cvt_pk_bf16_f32 v62, v56, v57
	ds_write_b16 v60, v62 offset:3536
	ds_write_b16_d16_hi v60, v62 offset:3664
	s_waitcnt lgkmcnt(15)
	v_fma_f32 v58, v36, v56, v118
	v_fma_f32 v59, v36, v57, v119
	v_mfma_f32_16x16x4_f32 v[24:27], v104, v88, 0
	v_mfma_f32_16x16x4_f32 v[28:31], v104, v89, 0
	v_fma_f32 v54, -v37, v57, v58
	v_fma_f32 v55, v37, v56, v59
	v_cvt_pk_bf16_f32 v62, v54, v55
	ds_write_b16 v60, v62 offset:3264
	ds_write_b16_d16_hi v60, v62 offset:3392
	s_waitcnt lgkmcnt(15)
	v_fma_f32 v58, v36, v54, v120
	v_fma_f32 v59, v36, v55, v121
	v_mfma_f32_16x16x4_f32 v[0:3], v105, v66, v[0:3]
	v_mfma_f32_16x16x4_f32 v[4:7], v105, v67, v[4:7]
	v_fma_f32 v56, -v37, v55, v58
	v_fma_f32 v57, v37, v54, v59
	v_cvt_pk_bf16_f32 v62, v56, v57
	ds_write_b16 v60, v62 offset:2992
	ds_write_b16_d16_hi v60, v62 offset:3120
	s_waitcnt lgkmcnt(15)
	v_fma_f32 v58, v36, v56, v122
	v_fma_f32 v59, v36, v57, v123
	v_mfma_f32_16x16x4_f32 v[8:11], v105, v74, v[8:11]
	v_mfma_f32_16x16x4_f32 v[12:15], v105, v75, v[12:15]
	v_fma_f32 v54, -v37, v57, v58
	v_fma_f32 v55, v37, v56, v59
	v_cvt_pk_bf16_f32 v62, v54, v55
	ds_write_b16 v60, v62 offset:2720
	ds_write_b16_d16_hi v60, v62 offset:2848
	s_waitcnt lgkmcnt(15)
	v_fma_f32 v58, v36, v54, v124
	v_fma_f32 v59, v36, v55, v125
	v_mfma_f32_16x16x4_f32 v[16:19], v105, v82, v[16:19]
	v_mfma_f32_16x16x4_f32 v[20:23], v105, v83, v[20:23]
	v_fma_f32 v56, -v37, v55, v58
	v_fma_f32 v57, v37, v54, v59
	v_cvt_pk_bf16_f32 v62, v56, v57
	ds_write_b16 v60, v62 offset:2448
	ds_write_b16_d16_hi v60, v62 offset:2576
	s_waitcnt lgkmcnt(15)
	v_fma_f32 v58, v36, v56, v126
	v_fma_f32 v59, v36, v57, v127
	v_mfma_f32_16x16x4_f32 v[24:27], v105, v90, v[24:27]
	v_mfma_f32_16x16x4_f32 v[28:31], v105, v91, v[28:31]
	v_fma_f32 v54, -v37, v57, v58
	v_fma_f32 v55, v37, v56, v59
	v_cvt_pk_bf16_f32 v62, v54, v55
	ds_write_b16 v60, v62 offset:2176
	ds_write_b16_d16_hi v60, v62 offset:2304
	s_waitcnt lgkmcnt(15)
	v_fma_f32 v58, v36, v54, v128
	v_fma_f32 v59, v36, v55, v129
	v_mfma_f32_16x16x4_f32 v[0:3], v106, v68, v[0:3]
	v_mfma_f32_16x16x4_f32 v[4:7], v106, v69, v[4:7]
	v_fma_f32 v56, -v37, v55, v58
	v_fma_f32 v57, v37, v54, v59
	v_cvt_pk_bf16_f32 v62, v56, v57
	ds_write_b16 v60, v62 offset:1904
	ds_write_b16_d16_hi v60, v62 offset:2032
	s_waitcnt lgkmcnt(15)
	v_fma_f32 v58, v36, v56, v130
	v_fma_f32 v59, v36, v57, v131
	v_mfma_f32_16x16x4_f32 v[8:11], v106, v76, v[8:11]
	v_mfma_f32_16x16x4_f32 v[12:15], v106, v77, v[12:15]
	v_fma_f32 v54, -v37, v57, v58
	v_fma_f32 v55, v37, v56, v59
	v_cvt_pk_bf16_f32 v62, v54, v55
	ds_write_b16 v60, v62 offset:1632
	ds_write_b16_d16_hi v60, v62 offset:1760
	s_waitcnt lgkmcnt(15)
	v_fma_f32 v58, v36, v54, v132
	v_fma_f32 v59, v36, v55, v133
	v_mfma_f32_16x16x4_f32 v[16:19], v106, v84, v[16:19]
	v_mfma_f32_16x16x4_f32 v[20:23], v106, v85, v[20:23]
	v_fma_f32 v56, -v37, v55, v58
	v_fma_f32 v57, v37, v54, v59
	v_cvt_pk_bf16_f32 v62, v56, v57
	ds_write_b16 v60, v62 offset:1360
	ds_write_b16_d16_hi v60, v62 offset:1488
	s_waitcnt lgkmcnt(15)
	v_fma_f32 v58, v36, v56, v134
	v_fma_f32 v59, v36, v57, v135
	v_mfma_f32_16x16x4_f32 v[24:27], v106, v92, v[24:27]
	v_mfma_f32_16x16x4_f32 v[28:31], v106, v93, v[28:31]
	v_fma_f32 v54, -v37, v57, v58
	v_fma_f32 v55, v37, v56, v59
	v_cvt_pk_bf16_f32 v62, v54, v55
	ds_write_b16 v60, v62 offset:1088
	ds_write_b16_d16_hi v60, v62 offset:1216
	s_waitcnt lgkmcnt(15)
	v_fma_f32 v58, v36, v54, v136
	v_fma_f32 v59, v36, v55, v137
	v_mfma_f32_16x16x4_f32 v[0:3], v107, v70, v[0:3]
	v_mfma_f32_16x16x4_f32 v[4:7], v107, v71, v[4:7]
	v_fma_f32 v56, -v37, v55, v58
	v_fma_f32 v57, v37, v54, v59
	v_cvt_pk_bf16_f32 v62, v56, v57
	ds_write_b16 v60, v62 offset:816
	ds_write_b16_d16_hi v60, v62 offset:944
	s_waitcnt lgkmcnt(15)
	v_fma_f32 v58, v36, v56, v138
	v_fma_f32 v59, v36, v57, v139
	v_mfma_f32_16x16x4_f32 v[8:11], v107, v78, v[8:11]
	v_mfma_f32_16x16x4_f32 v[12:15], v107, v79, v[12:15]
	v_fma_f32 v54, -v37, v57, v58
	v_fma_f32 v55, v37, v56, v59
	v_cvt_pk_bf16_f32 v62, v54, v55
	ds_write_b16 v60, v62 offset:544
	ds_write_b16_d16_hi v60, v62 offset:672
	s_waitcnt lgkmcnt(15)
	v_fma_f32 v58, v36, v54, v140
	v_fma_f32 v59, v36, v55, v141
	v_mfma_f32_16x16x4_f32 v[16:19], v107, v86, v[16:19]
	v_mfma_f32_16x16x4_f32 v[20:23], v107, v87, v[20:23]
	v_fma_f32 v56, -v37, v55, v58
	v_fma_f32 v57, v37, v54, v59
	v_cvt_pk_bf16_f32 v62, v56, v57
	ds_write_b16 v60, v62 offset:272
	ds_write_b16_d16_hi v60, v62 offset:400
	s_waitcnt lgkmcnt(15)
; __device__ void phase_s5_pass2(CParams& p, int l, int item, char* smem) {
;     ...
;     for (int s = 0; s < 4; s++) {
;       const int sb = dir == 0 ? s : 3 - s;
;       for (int i = 0; i < 16; i++) {
;         int tl = dir == 0 ? i : 15 - i;
;         int t = sb * 16 + tl;
;         float u[16];
; #pragma unroll
;         for (int k = 0; k < 4; k++) {
;           float4 uv = *(const float4*)(us + t * 16 + k * 4);
;           u[k * 4] = uv.x; u[k * 4 + 1] = uv.y; u[k * 4 + 2] = uv.z; u[k * 4 + 3] = uv.w;
;         }
;         f32x2 bu = {0.f, 0.f};
; #pragma unroll
;         for (int cc = 0; cc < 16; cc++) bu = __builtin_elementwise_fma(bb[cc], f32x2{u[cc], u[cc]}, bu);
;         float nr = A.x * hr - A.y * hi + bu[0];
;         float ni = A.x * hi + A.y * hr + bu[1];
;         hr = nr; hi = ni;
;         hs[tl * 136 + lane] = f2bf(hr);
;         hs[tl * 136 + 64 + lane] = f2bf(hi);
;       }
;       __syncthreads();
; #pragma unroll
;       for (int ks = 0; ks < 4; ks++) {
;         bf16x8 a = *(const bf16x8*)(hs + l15 * 136 + ks * 32 + lq * 8);
;         acc[sb] = __builtin_amdgcn_mfma_f32_16x16x32_bf16(a, cf[ks], acc[sb], 0, 0, 0);
;       }
	v_fma_f32 v58, v36, v56, v142
	v_fma_f32 v59, v36, v57, v143
	v_mfma_f32_16x16x4_f32 v[24:27], v107, v94, v[24:27]
	v_mfma_f32_16x16x4_f32 v[28:31], v107, v95, v[28:31]
	v_fma_f32 v54, -v37, v57, v58
	v_fma_f32 v55, v37, v56, v59
	v_cvt_pk_bf16_f32 v62, v54, v55
	ds_write_b16 v60, v62 offset:0
	ds_write_b16_d16_hi v60, v62 offset:128
	ds_read_b128 v[184:187], v61 offset:0
	ds_read_b128 v[188:191], v61 offset:64
	ds_read_b128 v[192:195], v61 offset:128
	ds_read_b128 v[196:199], v61 offset:192
	s_waitcnt lgkmcnt(0)
	v_mfma_f32_16x16x32_bf16 v[156:159], v[184:187], v[168:171], v[156:159]
	v_mfma_f32_16x16x32_bf16 v[156:159], v[188:191], v[172:175], v[156:159]
	v_mfma_f32_16x16x32_bf16 v[156:159], v[192:195], v[176:179], v[156:159]
	v_mfma_f32_16x16x32_bf16 v[156:159], v[196:199], v[180:183], v[156:159]
	s_nop 15
	s_nop 15
	ds_write2_b32 v44, v0, v4 offset0:0 offset1:1
	ds_write2_b32 v45, v1, v5 offset0:0 offset1:1
	ds_write2_b32 v46, v2, v6 offset0:0 offset1:1
	ds_write2_b32 v47, v3, v7 offset0:0 offset1:1
	ds_write2_b32 v44, v8, v12 offset0:32 offset1:33
	ds_write2_b32 v45, v9, v13 offset0:32 offset1:33
	ds_write2_b32 v46, v10, v14 offset0:32 offset1:33
	ds_write2_b32 v47, v11, v15 offset0:32 offset1:33
	ds_write2_b32 v44, v16, v20 offset0:64 offset1:65
	ds_write2_b32 v45, v17, v21 offset0:64 offset1:65
	ds_write2_b32 v46, v18, v22 offset0:64 offset1:65
	ds_write2_b32 v47, v19, v23 offset0:64 offset1:65
	ds_write2_b32 v44, v24, v28 offset0:96 offset1:97
	ds_write2_b32 v45, v25, v29 offset0:96 offset1:97
	ds_write2_b32 v46, v26, v30 offset0:96 offset1:97
	ds_write2_b32 v47, v27, v31 offset0:96 offset1:97
	ds_read_b64 v[0:1], v52 offset:0
	ds_read_b64 v[2:3], v52 offset:512
	ds_read_b64 v[4:5], v52 offset:1024
	ds_read_b64 v[6:7], v52 offset:1536
	ds_read_b64 v[8:9], v52 offset:2048
	ds_read_b64 v[10:11], v52 offset:2560
	ds_read_b64 v[12:13], v52 offset:3072
	ds_read_b64 v[14:15], v52 offset:3584
	ds_read_b64 v[16:17], v52 offset:4096
	ds_read_b64 v[18:19], v52 offset:4608
	ds_read_b64 v[20:21], v52 offset:5120
	ds_read_b64 v[22:23], v52 offset:5632
	ds_read_b64 v[24:25], v52 offset:6144
	ds_read_b64 v[26:27], v52 offset:6656
	ds_read_b64 v[28:29], v52 offset:7168
	ds_read_b64 v[30:31], v52 offset:7680
	s_waitcnt vmcnt(0)
	s_waitcnt lgkmcnt(15)
	v_fma_f32 v58, v36, v54, v0
	v_fma_f32 v59, v36, v55, v1
	v_mfma_f32_16x16x4_f32 v[112:115], v108, v64, 0
	v_mfma_f32_16x16x4_f32 v[116:119], v108, v65, 0
	v_fma_f32 v56, -v37, v55, v58
	v_fma_f32 v57, v37, v54, v59
	v_cvt_pk_bf16_f32 v62, v56, v57
	ds_write_b16 v60, v62 offset:4080
	ds_write_b16_d16_hi v60, v62 offset:4208
	s_waitcnt lgkmcnt(15)
	v_fma_f32 v58, v36, v56, v2
	v_fma_f32 v59, v36, v57, v3
	v_mfma_f32_16x16x4_f32 v[120:123], v108, v72, 0
	v_mfma_f32_16x16x4_f32 v[124:127], v108, v73, 0
	v_fma_f32 v54, -v37, v57, v58
	v_fma_f32 v55, v37, v56, v59
	v_cvt_pk_bf16_f32 v62, v54, v55
	ds_write_b16 v60, v62 offset:3808
	ds_write_b16_d16_hi v60, v62 offset:3936
	s_waitcnt lgkmcnt(15)
	v_fma_f32 v58, v36, v54, v4
	v_fma_f32 v59, v36, v55, v5
	v_mfma_f32_16x16x4_f32 v[128:131], v108, v80, 0
	v_mfma_f32_16x16x4_f32 v[132:135], v108, v81, 0
	v_fma_f32 v56, -v37, v55, v58
	v_fma_f32 v57, v37, v54, v59
	v_cvt_pk_bf16_f32 v62, v56, v57
	ds_write_b16 v60, v62 offset:3536
	ds_write_b16_d16_hi v60, v62 offset:3664
	s_waitcnt lgkmcnt(15)
	v_fma_f32 v58, v36, v56, v6
	v_fma_f32 v59, v36, v57, v7
	v_mfma_f32_16x16x4_f32 v[136:139], v108, v88, 0
	v_mfma_f32_16x16x4_f32 v[140:143], v108, v89, 0
	v_fma_f32 v54, -v37, v57, v58
	v_fma_f32 v55, v37, v56, v59
	v_cvt_pk_bf16_f32 v62, v54, v55
	ds_write_b16 v60, v62 offset:3264
	ds_write_b16_d16_hi v60, v62 offset:3392
	s_waitcnt lgkmcnt(15)
	v_fma_f32 v58, v36, v54, v8
	v_fma_f32 v59, v36, v55, v9
	v_mfma_f32_16x16x4_f32 v[112:115], v109, v66, v[112:115]
	v_mfma_f32_16x16x4_f32 v[116:119], v109, v67, v[116:119]
	v_fma_f32 v56, -v37, v55, v58
	v_fma_f32 v57, v37, v54, v59
	v_cvt_pk_bf16_f32 v62, v56, v57
	ds_write_b16 v60, v62 offset:2992
	ds_write_b16_d16_hi v60, v62 offset:3120
	s_waitcnt lgkmcnt(15)
	v_fma_f32 v58, v36, v56, v10
	v_fma_f32 v59, v36, v57, v11
	v_mfma_f32_16x16x4_f32 v[120:123], v109, v74, v[120:123]
	v_mfma_f32_16x16x4_f32 v[124:127], v109, v75, v[124:127]
	v_fma_f32 v54, -v37, v57, v58
	v_fma_f32 v55, v37, v56, v59
	v_cvt_pk_bf16_f32 v62, v54, v55
	ds_write_b16 v60, v62 offset:2720
	ds_write_b16_d16_hi v60, v62 offset:2848
	s_waitcnt lgkmcnt(15)
	v_fma_f32 v58, v36, v54, v12
	v_fma_f32 v59, v36, v55, v13
	v_mfma_f32_16x16x4_f32 v[128:131], v109, v82, v[128:131]
	v_mfma_f32_16x16x4_f32 v[132:135], v109, v83, v[132:135]
	v_fma_f32 v56, -v37, v55, v58
	v_fma_f32 v57, v37, v54, v59
	v_cvt_pk_bf16_f32 v62, v56, v57
	ds_write_b16 v60, v62 offset:2448
	ds_write_b16_d16_hi v60, v62 offset:2576
	s_waitcnt lgkmcnt(15)
	v_fma_f32 v58, v36, v56, v14
	v_fma_f32 v59, v36, v57, v15
	v_mfma_f32_16x16x4_f32 v[136:139], v109, v90, v[136:139]
	v_mfma_f32_16x16x4_f32 v[140:143], v109, v91, v[140:143]
	v_fma_f32 v54, -v37, v57, v58
	v_fma_f32 v55, v37, v56, v59
	v_cvt_pk_bf16_f32 v62, v54, v55
	ds_write_b16 v60, v62 offset:2176
	ds_write_b16_d16_hi v60, v62 offset:2304
	s_waitcnt lgkmcnt(15)
	v_fma_f32 v58, v36, v54, v16
	v_fma_f32 v59, v36, v55, v17
	v_mfma_f32_16x16x4_f32 v[112:115], v110, v68, v[112:115]
	v_mfma_f32_16x16x4_f32 v[116:119], v110, v69, v[116:119]
	v_fma_f32 v56, -v37, v55, v58
	v_fma_f32 v57, v37, v54, v59
	v_cvt_pk_bf16_f32 v62, v56, v57
	ds_write_b16 v60, v62 offset:1904
	ds_write_b16_d16_hi v60, v62 offset:2032
	s_waitcnt lgkmcnt(15)
; __device__ void phase_s5_pass2(CParams& p, int l, int item, char* smem) {
;     ...
;     for (int s = 0; s < 4; s++) {
;       const int sb = dir == 0 ? s : 3 - s;
;       for (int i = 0; i < 16; i++) {
;         int tl = dir == 0 ? i : 15 - i;
;         int t = sb * 16 + tl;
;         float u[16];
; #pragma unroll
;         for (int k = 0; k < 4; k++) {
;           float4 uv = *(const float4*)(us + t * 16 + k * 4);
;           u[k * 4] = uv.x; u[k * 4 + 1] = uv.y; u[k * 4 + 2] = uv.z; u[k * 4 + 3] = uv.w;
;         }
;         f32x2 bu = {0.f, 0.f};
; #pragma unroll
;         for (int cc = 0; cc < 16; cc++) bu = __builtin_elementwise_fma(bb[cc], f32x2{u[cc], u[cc]}, bu);
;         float nr = A.x * hr - A.y * hi + bu[0];
;         float ni = A.x * hi + A.y * hr + bu[1];
;         hr = nr; hi = ni;
;         hs[tl * 136 + lane] = f2bf(hr);
;         hs[tl * 136 + 64 + lane] = f2bf(hi);
;       }
;       __syncthreads();
; #pragma unroll
;       for (int ks = 0; ks < 4; ks++) {
;         bf16x8 a = *(const bf16x8*)(hs + l15 * 136 + ks * 32 + lq * 8);
;         acc[sb] = __builtin_amdgcn_mfma_f32_16x16x32_bf16(a, cf[ks], acc[sb], 0, 0, 0);
;       }
	v_fma_f32 v58, v36, v56, v18
	v_fma_f32 v59, v36, v57, v19
	v_mfma_f32_16x16x4_f32 v[120:123], v110, v76, v[120:123]
	v_mfma_f32_16x16x4_f32 v[124:127], v110, v77, v[124:127]
	v_fma_f32 v54, -v37, v57, v58
	v_fma_f32 v55, v37, v56, v59
	v_cvt_pk_bf16_f32 v62, v54, v55
	ds_write_b16 v60, v62 offset:1632
	ds_write_b16_d16_hi v60, v62 offset:1760
	s_waitcnt lgkmcnt(15)
	v_fma_f32 v58, v36, v54, v20
	v_fma_f32 v59, v36, v55, v21
	v_mfma_f32_16x16x4_f32 v[128:131], v110, v84, v[128:131]
	v_mfma_f32_16x16x4_f32 v[132:135], v110, v85, v[132:135]
	v_fma_f32 v56, -v37, v55, v58
	v_fma_f32 v57, v37, v54, v59
	v_cvt_pk_bf16_f32 v62, v56, v57
	ds_write_b16 v60, v62 offset:1360
	ds_write_b16_d16_hi v60, v62 offset:1488
	s_waitcnt lgkmcnt(15)
	v_fma_f32 v58, v36, v56, v22
	v_fma_f32 v59, v36, v57, v23
	v_mfma_f32_16x16x4_f32 v[136:139], v110, v92, v[136:139]
	v_mfma_f32_16x16x4_f32 v[140:143], v110, v93, v[140:143]
	v_fma_f32 v54, -v37, v57, v58
	v_fma_f32 v55, v37, v56, v59
	v_cvt_pk_bf16_f32 v62, v54, v55
	ds_write_b16 v60, v62 offset:1088
	ds_write_b16_d16_hi v60, v62 offset:1216
	s_waitcnt lgkmcnt(15)
	v_fma_f32 v58, v36, v54, v24
	v_fma_f32 v59, v36, v55, v25
	v_mfma_f32_16x16x4_f32 v[112:115], v111, v70, v[112:115]
	v_mfma_f32_16x16x4_f32 v[116:119], v111, v71, v[116:119]
	v_fma_f32 v56, -v37, v55, v58
	v_fma_f32 v57, v37, v54, v59
	v_cvt_pk_bf16_f32 v62, v56, v57
	ds_write_b16 v60, v62 offset:816
	ds_write_b16_d16_hi v60, v62 offset:944
	s_waitcnt lgkmcnt(15)
	v_fma_f32 v58, v36, v56, v26
	v_fma_f32 v59, v36, v57, v27
	v_mfma_f32_16x16x4_f32 v[120:123], v111, v78, v[120:123]
	v_mfma_f32_16x16x4_f32 v[124:127], v111, v79, v[124:127]
	v_fma_f32 v54, -v37, v57, v58
	v_fma_f32 v55, v37, v56, v59
	v_cvt_pk_bf16_f32 v62, v54, v55
	ds_write_b16 v60, v62 offset:544
	ds_write_b16_d16_hi v60, v62 offset:672
	s_waitcnt lgkmcnt(15)
	v_fma_f32 v58, v36, v54, v28
	v_fma_f32 v59, v36, v55, v29
	v_mfma_f32_16x16x4_f32 v[128:131], v111, v86, v[128:131]
	v_mfma_f32_16x16x4_f32 v[132:135], v111, v87, v[132:135]
	v_fma_f32 v56, -v37, v55, v58
	v_fma_f32 v57, v37, v54, v59
	v_cvt_pk_bf16_f32 v62, v56, v57
	ds_write_b16 v60, v62 offset:272
	ds_write_b16_d16_hi v60, v62 offset:400
	s_waitcnt lgkmcnt(15)
	v_fma_f32 v58, v36, v56, v30
	v_fma_f32 v59, v36, v57, v31
	v_mfma_f32_16x16x4_f32 v[136:139], v111, v94, v[136:139]
	v_mfma_f32_16x16x4_f32 v[140:143], v111, v95, v[140:143]
	v_fma_f32 v54, -v37, v57, v58
	v_fma_f32 v55, v37, v56, v59
	v_cvt_pk_bf16_f32 v62, v54, v55
	ds_write_b16 v60, v62 offset:0
	ds_write_b16_d16_hi v60, v62 offset:128
	ds_read_b128 v[184:187], v61 offset:0
	ds_read_b128 v[188:191], v61 offset:64
	ds_read_b128 v[192:195], v61 offset:128
	ds_read_b128 v[196:199], v61 offset:192
	s_waitcnt lgkmcnt(0)
	v_mfma_f32_16x16x32_bf16 v[152:155], v[184:187], v[168:171], v[152:155]
	v_mfma_f32_16x16x32_bf16 v[152:155], v[188:191], v[172:175], v[152:155]
	v_mfma_f32_16x16x32_bf16 v[152:155], v[192:195], v[176:179], v[152:155]
	v_mfma_f32_16x16x32_bf16 v[152:155], v[196:199], v[180:183], v[152:155]
	s_nop 15
	s_nop 15
	ds_write2_b32 v44, v112, v116 offset0:0 offset1:1
	ds_write2_b32 v45, v113, v117 offset0:0 offset1:1
	ds_write2_b32 v46, v114, v118 offset0:0 offset1:1
	ds_write2_b32 v47, v115, v119 offset0:0 offset1:1
	ds_write2_b32 v44, v120, v124 offset0:32 offset1:33
	ds_write2_b32 v45, v121, v125 offset0:32 offset1:33
	ds_write2_b32 v46, v122, v126 offset0:32 offset1:33
	ds_write2_b32 v47, v123, v127 offset0:32 offset1:33
	ds_write2_b32 v44, v128, v132 offset0:64 offset1:65
	ds_write2_b32 v45, v129, v133 offset0:64 offset1:65
	ds_write2_b32 v46, v130, v134 offset0:64 offset1:65
	ds_write2_b32 v47, v131, v135 offset0:64 offset1:65
	ds_write2_b32 v44, v136, v140 offset0:96 offset1:97
	ds_write2_b32 v45, v137, v141 offset0:96 offset1:97
	ds_write2_b32 v46, v138, v142 offset0:96 offset1:97
	ds_write2_b32 v47, v139, v143 offset0:96 offset1:97
	ds_read_b64 v[112:113], v52 offset:0
	ds_read_b64 v[114:115], v52 offset:512
	ds_read_b64 v[116:117], v52 offset:1024
	ds_read_b64 v[118:119], v52 offset:1536
	ds_read_b64 v[120:121], v52 offset:2048
	ds_read_b64 v[122:123], v52 offset:2560
	ds_read_b64 v[124:125], v52 offset:3072
	ds_read_b64 v[126:127], v52 offset:3584
	ds_read_b64 v[128:129], v52 offset:4096
	ds_read_b64 v[130:131], v52 offset:4608
	ds_read_b64 v[132:133], v52 offset:5120
	ds_read_b64 v[134:135], v52 offset:5632
	ds_read_b64 v[136:137], v52 offset:6144
	ds_read_b64 v[138:139], v52 offset:6656
	ds_read_b64 v[140:141], v52 offset:7168
	ds_read_b64 v[142:143], v52 offset:7680
	s_waitcnt lgkmcnt(15)
	v_fma_f32 v58, v36, v54, v112
	v_fma_f32 v59, v36, v55, v113
	v_fma_f32 v56, -v37, v55, v58
	v_fma_f32 v57, v37, v54, v59
	v_cvt_pk_bf16_f32 v62, v56, v57
	ds_write_b16 v60, v62 offset:4080
	ds_write_b16_d16_hi v60, v62 offset:4208
	s_waitcnt lgkmcnt(15)
	v_fma_f32 v58, v36, v56, v114
	v_fma_f32 v59, v36, v57, v115
	v_fma_f32 v54, -v37, v57, v58
	v_fma_f32 v55, v37, v56, v59
	v_cvt_pk_bf16_f32 v62, v54, v55
	ds_write_b16 v60, v62 offset:3808
	ds_write_b16_d16_hi v60, v62 offset:3936
	s_waitcnt lgkmcnt(15)
	v_fma_f32 v58, v36, v54, v116
	v_fma_f32 v59, v36, v55, v117
	v_fma_f32 v56, -v37, v55, v58
	v_fma_f32 v57, v37, v54, v59
	v_cvt_pk_bf16_f32 v62, v56, v57
	ds_write_b16 v60, v62 offset:3536
	ds_write_b16_d16_hi v60, v62 offset:3664
	s_waitcnt lgkmcnt(15)
	v_fma_f32 v58, v36, v56, v118
	v_fma_f32 v59, v36, v57, v119
	v_fma_f32 v54, -v37, v57, v58
	v_fma_f32 v55, v37, v56, v59
	v_cvt_pk_bf16_f32 v62, v54, v55
	ds_write_b16 v60, v62 offset:3264
	ds_write_b16_d16_hi v60, v62 offset:3392
	s_waitcnt lgkmcnt(15)
; __device__ void phase_s5_pass2(CParams& p, int l, int item, char* smem) {
;     ...
;     for (int s = 0; s < 4; s++) {
;       const int sb = dir == 0 ? s : 3 - s;
;       for (int i = 0; i < 16; i++) {
;         int tl = dir == 0 ? i : 15 - i;
;         int t = sb * 16 + tl;
;         float u[16];
; #pragma unroll
;         for (int k = 0; k < 4; k++) {
;           float4 uv = *(const float4*)(us + t * 16 + k * 4);
;           u[k * 4] = uv.x; u[k * 4 + 1] = uv.y; u[k * 4 + 2] = uv.z; u[k * 4 + 3] = uv.w;
;         }
;         f32x2 bu = {0.f, 0.f};
; #pragma unroll
;         for (int cc = 0; cc < 16; cc++) bu = __builtin_elementwise_fma(bb[cc], f32x2{u[cc], u[cc]}, bu);
;         float nr = A.x * hr - A.y * hi + bu[0];
;         float ni = A.x * hi + A.y * hr + bu[1];
;         hr = nr; hi = ni;
;         hs[tl * 136 + lane] = f2bf(hr);
;         hs[tl * 136 + 64 + lane] = f2bf(hi);
;       }
;       __syncthreads();
; #pragma unroll
;       for (int ks = 0; ks < 4; ks++) {
;         bf16x8 a = *(const bf16x8*)(hs + l15 * 136 + ks * 32 + lq * 8);
;         acc[sb] = __builtin_amdgcn_mfma_f32_16x16x32_bf16(a, cf[ks], acc[sb], 0, 0, 0);
;       }
;     ...
;   float dd = p.s5d[l * 256 + g * 16 + l15];
; #pragma unroll
;   for (int sb = 0; sb < 4; sb++)
; #pragma unroll
;     for (int j = 0; j < 4; j++) {
;       int t = sb * 16 + lq * 4 + j;
;       float y = acc[sb][j] + dd * us[t * 16 + l15];
	v_fma_f32 v58, v36, v54, v120
	v_fma_f32 v59, v36, v55, v121
	v_fma_f32 v56, -v37, v55, v58
	v_fma_f32 v57, v37, v54, v59
	v_cvt_pk_bf16_f32 v62, v56, v57
	ds_write_b16 v60, v62 offset:2992
	ds_write_b16_d16_hi v60, v62 offset:3120
	s_waitcnt lgkmcnt(15)
	v_fma_f32 v58, v36, v56, v122
	v_fma_f32 v59, v36, v57, v123
	v_fma_f32 v54, -v37, v57, v58
	v_fma_f32 v55, v37, v56, v59
	v_cvt_pk_bf16_f32 v62, v54, v55
	ds_write_b16 v60, v62 offset:2720
	ds_write_b16_d16_hi v60, v62 offset:2848
	s_waitcnt lgkmcnt(15)
	v_fma_f32 v58, v36, v54, v124
	v_fma_f32 v59, v36, v55, v125
	v_fma_f32 v56, -v37, v55, v58
	v_fma_f32 v57, v37, v54, v59
	v_cvt_pk_bf16_f32 v62, v56, v57
	ds_write_b16 v60, v62 offset:2448
	ds_write_b16_d16_hi v60, v62 offset:2576
	s_waitcnt lgkmcnt(15)
	v_fma_f32 v58, v36, v56, v126
	v_fma_f32 v59, v36, v57, v127
	v_fma_f32 v54, -v37, v57, v58
	v_fma_f32 v55, v37, v56, v59
	v_cvt_pk_bf16_f32 v62, v54, v55
	ds_write_b16 v60, v62 offset:2176
	ds_write_b16_d16_hi v60, v62 offset:2304
	s_waitcnt lgkmcnt(15)
	v_fma_f32 v58, v36, v54, v128
	v_fma_f32 v59, v36, v55, v129
	v_fma_f32 v56, -v37, v55, v58
	v_fma_f32 v57, v37, v54, v59
	v_cvt_pk_bf16_f32 v62, v56, v57
	ds_write_b16 v60, v62 offset:1904
	ds_write_b16_d16_hi v60, v62 offset:2032
	s_waitcnt lgkmcnt(15)
	v_fma_f32 v58, v36, v56, v130
	v_fma_f32 v59, v36, v57, v131
	v_fma_f32 v54, -v37, v57, v58
	v_fma_f32 v55, v37, v56, v59
	v_cvt_pk_bf16_f32 v62, v54, v55
	ds_write_b16 v60, v62 offset:1632
	ds_write_b16_d16_hi v60, v62 offset:1760
	s_waitcnt lgkmcnt(15)
	v_fma_f32 v58, v36, v54, v132
	v_fma_f32 v59, v36, v55, v133
	v_fma_f32 v56, -v37, v55, v58
	v_fma_f32 v57, v37, v54, v59
	v_cvt_pk_bf16_f32 v62, v56, v57
	ds_write_b16 v60, v62 offset:1360
	ds_write_b16_d16_hi v60, v62 offset:1488
	s_waitcnt lgkmcnt(15)
	v_fma_f32 v58, v36, v56, v134
	v_fma_f32 v59, v36, v57, v135
	v_fma_f32 v54, -v37, v57, v58
	v_fma_f32 v55, v37, v56, v59
	v_cvt_pk_bf16_f32 v62, v54, v55
	ds_write_b16 v60, v62 offset:1088
	ds_write_b16_d16_hi v60, v62 offset:1216
	s_waitcnt lgkmcnt(15)
	v_fma_f32 v58, v36, v54, v136
	v_fma_f32 v59, v36, v55, v137
	v_fma_f32 v56, -v37, v55, v58
	v_fma_f32 v57, v37, v54, v59
	v_cvt_pk_bf16_f32 v62, v56, v57
	ds_write_b16 v60, v62 offset:816
	ds_write_b16_d16_hi v60, v62 offset:944
	s_waitcnt lgkmcnt(15)
	v_fma_f32 v58, v36, v56, v138
	v_fma_f32 v59, v36, v57, v139
	v_fma_f32 v54, -v37, v57, v58
	v_fma_f32 v55, v37, v56, v59
	v_cvt_pk_bf16_f32 v62, v54, v55
	ds_write_b16 v60, v62 offset:544
	ds_write_b16_d16_hi v60, v62 offset:672
	s_waitcnt lgkmcnt(15)
	v_fma_f32 v58, v36, v54, v140
	v_fma_f32 v59, v36, v55, v141
	v_fma_f32 v56, -v37, v55, v58
	v_fma_f32 v57, v37, v54, v59
	v_cvt_pk_bf16_f32 v62, v56, v57
	ds_write_b16 v60, v62 offset:272
	ds_write_b16_d16_hi v60, v62 offset:400
	s_waitcnt lgkmcnt(15)
	v_fma_f32 v58, v36, v56, v142
	v_fma_f32 v59, v36, v57, v143
	v_fma_f32 v54, -v37, v57, v58
	v_fma_f32 v55, v37, v56, v59
	v_cvt_pk_bf16_f32 v62, v54, v55
	ds_write_b16 v60, v62 offset:0
	ds_write_b16_d16_hi v60, v62 offset:128
	ds_read_b128 v[184:187], v61 offset:0
	ds_read_b128 v[188:191], v61 offset:64
	ds_read_b128 v[192:195], v61 offset:128
	ds_read_b128 v[196:199], v61 offset:192
	s_waitcnt lgkmcnt(0)
	v_mfma_f32_16x16x32_bf16 v[148:151], v[184:187], v[168:171], v[148:151]
	v_mfma_f32_16x16x32_bf16 v[148:151], v[188:191], v[172:175], v[148:151]
	v_mfma_f32_16x16x32_bf16 v[148:151], v[192:195], v[176:179], v[148:151]
	v_mfma_f32_16x16x32_bf16 v[148:151], v[196:199], v[180:183], v[148:151]
	s_load_dwordx2 s[92:93], s[44:45], 0x78
	s_lshl_b32 s20, s12, 8
	s_lshl_b32 s32, s2, 4
	s_add_u32 s20, s20, s32
	s_lshl_b32 s20, s20, 2
	v_lshlrev_b32_e32 v38, 2, v33
	s_waitcnt lgkmcnt(0)
	s_add_u32 s92, s92, s20
	s_addc_u32 s93, s93, 0
	global_load_dword v50, v38, s[92:93]
	global_load_dword v200, v63, s[6:7] offset:0
	global_load_dword v201, v63, s[6:7] offset:1024
	global_load_dword v202, v63, s[6:7] offset:2048
	global_load_dword v203, v63, s[6:7] offset:3072
	s_add_u32 s6, s6, 0x4000
	s_addc_u32 s7, s7, 0
	global_load_dword v204, v63, s[6:7] offset:0
	global_load_dword v205, v63, s[6:7] offset:1024
	global_load_dword v206, v63, s[6:7] offset:2048
	global_load_dword v207, v63, s[6:7] offset:3072
	s_add_u32 s6, s6, 0x4000
	s_addc_u32 s7, s7, 0
	global_load_dword v208, v63, s[6:7] offset:0
	global_load_dword v209, v63, s[6:7] offset:1024
	global_load_dword v210, v63, s[6:7] offset:2048
	global_load_dword v211, v63, s[6:7] offset:3072
	s_add_u32 s6, s6, 0x4000
	s_addc_u32 s7, s7, 0
	global_load_dword v212, v63, s[6:7] offset:0
	global_load_dword v213, v63, s[6:7] offset:1024
	global_load_dword v214, v63, s[6:7] offset:2048
	global_load_dword v215, v63, s[6:7] offset:3072
	s_nop 7
	s_waitcnt vmcnt(0)
; __device__ void phase_s5_pass2(CParams& p, int l, int item, char* smem) {
;     ...
;   float dd = p.s5d[l * 256 + g * 16 + l15];
; #pragma unroll
;   for (int sb = 0; sb < 4; sb++)
; #pragma unroll
;     for (int j = 0; j < 4; j++) {
;       int t = sb * 16 + lq * 4 + j;
;       float y = acc[sb][j] + dd * us[t * 16 + l15];
;       float z = 0.7978845608028654f * (y + 0.044715f * y * y * y);
;       float ge = y / (1.f + __expf(-2.f * z));
;       p.ys[(size_t)(tok0 + t) * 256 + g * 16 + l15] = f2bf(ge);
;     }
	v_fmac_f32_e32 v148, v50, v200
	v_mul_f32_e32 v200, v148, v148
	v_mul_f32_e32 v200, v200, v148
	v_mov_b32_e32 v39, 0x3d372713
	v_fma_f32 v200, v200, v39, v148
	v_mul_f32_e32 v200, 0xc0135761, v200
	v_exp_f32_e32 v200, v200
	s_nop 0
	v_add_f32_e32 v200, 1.0, v200
	v_rcp_f32_e32 v200, v200
	s_nop 0
	v_mul_f32_e32 v200, v200, v148
	v_cvt_pk_bf16_f32 v200, v200, v200
	global_store_short v48, v200, s[8:9] offset:0
	v_fmac_f32_e32 v149, v50, v201
	v_mul_f32_e32 v201, v149, v149
	v_mul_f32_e32 v201, v201, v149
	v_mov_b32_e32 v39, 0x3d372713
	v_fma_f32 v201, v201, v39, v149
	v_mul_f32_e32 v201, 0xc0135761, v201
	v_exp_f32_e32 v201, v201
	s_nop 0
	v_add_f32_e32 v201, 1.0, v201
	v_rcp_f32_e32 v201, v201
	s_nop 0
	v_mul_f32_e32 v201, v201, v149
	v_cvt_pk_bf16_f32 v201, v201, v201
	global_store_short v48, v201, s[8:9] offset:512
	v_fmac_f32_e32 v150, v50, v202
	v_mul_f32_e32 v202, v150, v150
	v_mul_f32_e32 v202, v202, v150
	v_mov_b32_e32 v39, 0x3d372713
	v_fma_f32 v202, v202, v39, v150
	v_mul_f32_e32 v202, 0xc0135761, v202
	v_exp_f32_e32 v202, v202
	s_nop 0
	v_add_f32_e32 v202, 1.0, v202
	v_rcp_f32_e32 v202, v202
	s_nop 0
	v_mul_f32_e32 v202, v202, v150
	v_cvt_pk_bf16_f32 v202, v202, v202
	global_store_short v48, v202, s[8:9] offset:1024
	v_fmac_f32_e32 v151, v50, v203
	v_mul_f32_e32 v203, v151, v151
	v_mul_f32_e32 v203, v203, v151
	v_mov_b32_e32 v39, 0x3d372713
	v_fma_f32 v203, v203, v39, v151
	v_mul_f32_e32 v203, 0xc0135761, v203
	v_exp_f32_e32 v203, v203
	s_nop 0
	v_add_f32_e32 v203, 1.0, v203
	v_rcp_f32_e32 v203, v203
	s_nop 0
	v_mul_f32_e32 v203, v203, v151
	v_cvt_pk_bf16_f32 v203, v203, v203
	global_store_short v48, v203, s[8:9] offset:1536
	s_add_u32 s8, s8, 0x2000
	s_addc_u32 s9, s9, 0
	v_fmac_f32_e32 v152, v50, v204
	v_mul_f32_e32 v204, v152, v152
	v_mul_f32_e32 v204, v204, v152
	v_mov_b32_e32 v39, 0x3d372713
	v_fma_f32 v204, v204, v39, v152
	v_mul_f32_e32 v204, 0xc0135761, v204
	v_exp_f32_e32 v204, v204
	s_nop 0
	v_add_f32_e32 v204, 1.0, v204
	v_rcp_f32_e32 v204, v204
	s_nop 0
	v_mul_f32_e32 v204, v204, v152
	v_cvt_pk_bf16_f32 v204, v204, v204
	global_store_short v48, v204, s[8:9] offset:0
	v_fmac_f32_e32 v153, v50, v205
	v_mul_f32_e32 v205, v153, v153
	v_mul_f32_e32 v205, v205, v153
	v_mov_b32_e32 v39, 0x3d372713
	v_fma_f32 v205, v205, v39, v153
	v_mul_f32_e32 v205, 0xc0135761, v205
	v_exp_f32_e32 v205, v205
	s_nop 0
	v_add_f32_e32 v205, 1.0, v205
	v_rcp_f32_e32 v205, v205
	s_nop 0
	v_mul_f32_e32 v205, v205, v153
	v_cvt_pk_bf16_f32 v205, v205, v205
	global_store_short v48, v205, s[8:9] offset:512
	v_fmac_f32_e32 v154, v50, v206
	v_mul_f32_e32 v206, v154, v154
	v_mul_f32_e32 v206, v206, v154
	v_mov_b32_e32 v39, 0x3d372713
	v_fma_f32 v206, v206, v39, v154
	v_mul_f32_e32 v206, 0xc0135761, v206
	v_exp_f32_e32 v206, v206
	s_nop 0
	v_add_f32_e32 v206, 1.0, v206
	v_rcp_f32_e32 v206, v206
	s_nop 0
	v_mul_f32_e32 v206, v206, v154
	v_cvt_pk_bf16_f32 v206, v206, v206
	global_store_short v48, v206, s[8:9] offset:1024
	v_fmac_f32_e32 v155, v50, v207
	v_mul_f32_e32 v207, v155, v155
	v_mul_f32_e32 v207, v207, v155
	v_mov_b32_e32 v39, 0x3d372713
	v_fma_f32 v207, v207, v39, v155
	v_mul_f32_e32 v207, 0xc0135761, v207
	v_exp_f32_e32 v207, v207
	s_nop 0
	v_add_f32_e32 v207, 1.0, v207
	v_rcp_f32_e32 v207, v207
	s_nop 0
	v_mul_f32_e32 v207, v207, v155
	v_cvt_pk_bf16_f32 v207, v207, v207
	global_store_short v48, v207, s[8:9] offset:1536
	s_add_u32 s8, s8, 0x2000
	s_addc_u32 s9, s9, 0
	v_fmac_f32_e32 v156, v50, v208
	v_mul_f32_e32 v208, v156, v156
	v_mul_f32_e32 v208, v208, v156
	v_mov_b32_e32 v39, 0x3d372713
	v_fma_f32 v208, v208, v39, v156
	v_mul_f32_e32 v208, 0xc0135761, v208
	v_exp_f32_e32 v208, v208
	s_nop 0
	v_add_f32_e32 v208, 1.0, v208
	v_rcp_f32_e32 v208, v208
	s_nop 0
	v_mul_f32_e32 v208, v208, v156
	v_cvt_pk_bf16_f32 v208, v208, v208
	global_store_short v48, v208, s[8:9] offset:0
	v_fmac_f32_e32 v157, v50, v209
	v_mul_f32_e32 v209, v157, v157
	v_mul_f32_e32 v209, v209, v157
	v_mov_b32_e32 v39, 0x3d372713
	v_fma_f32 v209, v209, v39, v157
	v_mul_f32_e32 v209, 0xc0135761, v209
	v_exp_f32_e32 v209, v209
	s_nop 0
	v_add_f32_e32 v209, 1.0, v209
	v_rcp_f32_e32 v209, v209
	s_nop 0
	v_mul_f32_e32 v209, v209, v157
	v_cvt_pk_bf16_f32 v209, v209, v209
	global_store_short v48, v209, s[8:9] offset:512
	v_fmac_f32_e32 v158, v50, v210
	v_mul_f32_e32 v210, v158, v158
	v_mul_f32_e32 v210, v210, v158
	v_mov_b32_e32 v39, 0x3d372713
	v_fma_f32 v210, v210, v39, v158
	v_mul_f32_e32 v210, 0xc0135761, v210
	v_exp_f32_e32 v210, v210
	s_nop 0
	v_add_f32_e32 v210, 1.0, v210
	v_rcp_f32_e32 v210, v210
	s_nop 0
	v_mul_f32_e32 v210, v210, v158
	v_cvt_pk_bf16_f32 v210, v210, v210
	global_store_short v48, v210, s[8:9] offset:1024
	v_fmac_f32_e32 v159, v50, v211
	v_mul_f32_e32 v211, v159, v159
	v_mul_f32_e32 v211, v211, v159
	v_mov_b32_e32 v39, 0x3d372713
	v_fma_f32 v211, v211, v39, v159
	v_mul_f32_e32 v211, 0xc0135761, v211
	v_exp_f32_e32 v211, v211
	s_nop 0
	v_add_f32_e32 v211, 1.0, v211
	v_rcp_f32_e32 v211, v211
	s_nop 0
	v_mul_f32_e32 v211, v211, v159
	v_cvt_pk_bf16_f32 v211, v211, v211
	global_store_short v48, v211, s[8:9] offset:1536
	s_add_u32 s8, s8, 0x2000
	s_addc_u32 s9, s9, 0
	v_fmac_f32_e32 v160, v50, v212
	v_mul_f32_e32 v212, v160, v160
	v_mul_f32_e32 v212, v212, v160
	v_mov_b32_e32 v39, 0x3d372713
	v_fma_f32 v212, v212, v39, v160
	v_mul_f32_e32 v212, 0xc0135761, v212
	v_exp_f32_e32 v212, v212
	s_nop 0
	v_add_f32_e32 v212, 1.0, v212
	v_rcp_f32_e32 v212, v212
	s_nop 0
	v_mul_f32_e32 v212, v212, v160
	v_cvt_pk_bf16_f32 v212, v212, v212
	global_store_short v48, v212, s[8:9] offset:0
	v_fmac_f32_e32 v161, v50, v213
	v_mul_f32_e32 v213, v161, v161
	v_mul_f32_e32 v213, v213, v161
	v_mov_b32_e32 v39, 0x3d372713
	v_fma_f32 v213, v213, v39, v161
	v_mul_f32_e32 v213, 0xc0135761, v213
	v_exp_f32_e32 v213, v213
	s_nop 0
	v_add_f32_e32 v213, 1.0, v213
	v_rcp_f32_e32 v213, v213
	s_nop 0
	v_mul_f32_e32 v213, v213, v161
	v_cvt_pk_bf16_f32 v213, v213, v213
	global_store_short v48, v213, s[8:9] offset:512
	v_fmac_f32_e32 v162, v50, v214
	v_mul_f32_e32 v214, v162, v162
	v_mul_f32_e32 v214, v214, v162
	v_mov_b32_e32 v39, 0x3d372713
	v_fma_f32 v214, v214, v39, v162
	v_mul_f32_e32 v214, 0xc0135761, v214
	v_exp_f32_e32 v214, v214
	s_nop 0
	v_add_f32_e32 v214, 1.0, v214
	v_rcp_f32_e32 v214, v214
	s_nop 0
	v_mul_f32_e32 v214, v214, v162
	v_cvt_pk_bf16_f32 v214, v214, v214
	global_store_short v48, v214, s[8:9] offset:1024
	v_fmac_f32_e32 v163, v50, v215
	v_mul_f32_e32 v215, v163, v163
	v_mul_f32_e32 v215, v215, v163
	v_mov_b32_e32 v39, 0x3d372713
	v_fma_f32 v215, v215, v39, v163
	v_mul_f32_e32 v215, 0xc0135761, v215
	v_exp_f32_e32 v215, v215
	s_nop 0
	v_add_f32_e32 v215, 1.0, v215
	v_rcp_f32_e32 v215, v215
	s_nop 0
	v_mul_f32_e32 v215, v215, v163
	v_cvt_pk_bf16_f32 v215, v215, v215
	global_store_short v48, v215, s[8:9] offset:1536
	s_waitcnt lgkmcnt(0)
	s_barrier
	s_branch .LBB0_686
